# final y stores nt
# baseline (speedup 1.0000x reference)
;     __device__ __forceinline__ void operator()(const f32x4 (&acc)[2][2][4][2], const Unit& u_, int wr, int wc, int fr, int fq) const {
;     ...
;         for (int bj = 0; bj < 2; ++bj) g4[bj] = *(const f32x4*)(pg + colb + bj * HALF);
; #pragma unroll
;         for (int am = 0; am < 4; ++am) { const int ai = am >> 1, m0 = (am & 1) * 2;
;             u32x2 hb[2][2][2], eb[2][2][2]; float sq[2][2];
; #pragma unroll
;             for (int m = 0; m < 2; ++m)
; #pragma unroll
;                 for (int t = 0; t < 2; ++t) { const int row = rowb + ai * HALF + (m0 + m) * 16 + 8 * t; const size_t off = (size_t)row * 1024 + colb; sq[m][t] = ssq[row];
; #pragma unroll
;                     for (int bj = 0; bj < 2; ++bj) { hb[m][bj][t] = *(const u32x2*)(h1b + off + bj * HALF); eb[m][bj][t] = *(const u32x2*)(E + off + bj * HALF); } }
;             asm volatile("" ::: "memory");
; #pragma unroll
;             for (int m = 0; m < 2; ++m) {
;                 const float rstd[2] = {__builtin_amdgcn_rsqf(sq[m][0] * (1.0f / 1024.0f) + 1e-6f), __builtin_amdgcn_rsqf(sq[m][1] * (1.0f / 1024.0f) + 1e-6f)};
; #pragma unroll
;                 for (int bj = 0; bj < 2; ++bj) { f32x4 a[2]; xchg_f32(xl, fr, fq, l, acc[ai][bj][m0 + m][0], acc[ai][bj][m0 + m][1], a[0], a[1]);
; #pragma unroll
;                     for (int t = 0; t < 2; ++t) { const unsigned hw[2] = {hb[m][bj][t].x, hb[m][bj][t].y}, ew[2] = {eb[m][bj][t].x, eb[m][bj][t].y};
;                         f32x4 o;
; #pragma unroll
;                         for (int i = 0; i < 4; ++i) { const float h = (i & 1) ? __uint_as_float(hw[i >> 1] & 0xffff0000u) : __uint_as_float(hw[i >> 1] << 16);
;                             const float ee = (i & 1) ? __uint_as_float(ew[i >> 1] & 0xffff0000u) : __uint_as_float(ew[i >> 1] << 16);
;                             const float sg = __builtin_amdgcn_rcpf(1.0f + __expf(-a[t][i]));
;                             o[i] = h + sg * (ee * rstd[t] * g4[bj][i]); }
;                         *(f32x4*)(y + (size_t)(rowb + ai * HALF + (m0 + m) * 16 + 8 * t) * 1024 + colb + bj * HALF) = o; } } }
.LBB0_903:
	s_mov_b64 s[56:57], -1
	v_lshl_or_b32 v150, s8, 8, v205
	v_lshl_add_u32 v152, s2, 8, v206
	v_ashrrev_i32_e32 v151, 31, v150
	v_ashrrev_i32_e32 v153, 31, v152
	v_lshlrev_b64 v[148:149], 2, v[150:151]
	v_lshlrev_b64 v[154:155], 10, v[152:153]
	v_lshl_add_u64 v[26:27], s[94:95], 0, v[148:149]
	v_lshl_add_u64 v[156:157], v[154:155], 0, v[150:151]
	v_lshl_add_u64 v[154:155], v[152:153], 2, s[20:21]
	global_load_dwordx4 v[38:41], v[26:27], off
	s_nop 0
	global_load_dwordx4 v[26:29], v[26:27], off offset:512
	v_lshlrev_b64 v[156:157], 1, v[156:157]
	global_load_dword v198, v[154:155], off
	v_or_b32_e32 v184, 8, v152
	v_lshl_add_u64 v[158:159], s[14:15], 0, v[156:157]
	v_ashrrev_i32_e32 v185, 31, v184
	v_lshl_add_u64 v[156:157], s[18:19], 0, v[156:157]
	global_load_dwordx2 v[202:203], v[158:159], off
	global_load_dwordx2 v[200:201], v[156:157], off
	global_load_dwordx2 v[182:183], v[158:159], off offset:256
	global_load_dwordx2 v[180:181], v[156:157], off offset:256
	v_lshl_add_u64 v[158:159], v[184:185], 2, s[20:21]
	global_load_dword v214, v[158:159], off
	v_lshlrev_b64 v[156:157], 10, v[184:185]
	v_lshl_add_u64 v[156:157], v[156:157], 0, v[150:151]
	v_lshlrev_b64 v[156:157], 1, v[156:157]
	v_lshl_add_u64 v[158:159], s[14:15], 0, v[156:157]
	v_lshl_add_u64 v[156:157], s[18:19], 0, v[156:157]
	global_load_dwordx2 v[196:197], v[158:159], off
	global_load_dwordx2 v[194:195], v[156:157], off
	global_load_dwordx2 v[174:175], v[158:159], off offset:256
	global_load_dwordx2 v[172:173], v[156:157], off offset:256
	v_or_b32_e32 v166, 16, v152
	v_ashrrev_i32_e32 v167, 31, v166
	v_lshl_add_u64 v[158:159], v[166:167], 2, s[20:21]
	v_or_b32_e32 v164, 24, v152
	v_lshlrev_b64 v[156:157], 10, v[166:167]
	global_load_dword v210, v[158:159], off
	v_ashrrev_i32_e32 v165, 31, v164
	v_lshl_add_u64 v[156:157], v[156:157], 0, v[150:151]
	v_lshlrev_b64 v[160:161], 10, v[164:165]
	v_lshlrev_b64 v[156:157], 1, v[156:157]
	v_lshl_add_u64 v[160:161], v[160:161], 0, v[150:151]
	v_lshl_add_u64 v[158:159], s[14:15], 0, v[156:157]
	v_lshl_add_u64 v[156:157], s[18:19], 0, v[156:157]
	v_lshl_add_u64 v[162:163], v[164:165], 2, s[20:21]
	v_lshlrev_b64 v[160:161], 1, v[160:161]
	global_load_dwordx2 v[170:171], v[158:159], off
	global_load_dwordx2 v[168:169], v[156:157], off
	s_nop 0
	global_load_dwordx2 v[158:159], v[158:159], off offset:256
	s_nop 0
	global_load_dwordx2 v[156:157], v[156:157], off offset:256
	v_lshl_add_u64 v[212:213], s[18:19], 0, v[160:161]
	global_load_dword v211, v[162:163], off
	v_lshl_add_u64 v[162:163], s[14:15], 0, v[160:161]
	global_load_dwordx2 v[178:179], v[162:163], off
	global_load_dwordx2 v[176:177], v[212:213], off
	global_load_dwordx2 v[160:161], v[162:163], off offset:256
	s_nop 0
	global_load_dwordx2 v[162:163], v[212:213], off offset:256
	ds_write_b128 v208, v[134:137]
	ds_write_b128 v208, v[130:133] offset:16
	ds_read_b128 v[134:137], v209
	ds_read_b128 v[130:133], v209 offset:1152
	s_cmp_eq_u32 s23, s82
	s_waitcnt lgkmcnt(0)
	v_mul_f32_e32 v136, 0xbfb8aa3b, v136
	v_mul_f32_e32 v137, 0xbfb8aa3b, v137
	v_exp_f32_e32 v136, v136
	v_exp_f32_e32 v137, v137
	v_mul_f32_e32 v134, 0xbfb8aa3b, v134
	v_mul_f32_e32 v135, 0xbfb8aa3b, v135
	v_exp_f32_e32 v134, v134
	v_exp_f32_e32 v135, v135
	v_add_f32_e32 v136, 1.0, v136
	v_add_f32_e32 v137, 1.0, v137
	v_rcp_f32_e32 v136, v136
	v_rcp_f32_e32 v137, v137
	v_mul_f32_e32 v130, 0xbfb8aa3b, v130
	v_mul_f32_e32 v131, 0xbfb8aa3b, v131
	v_add_f32_e32 v134, 1.0, v134
	v_add_f32_e32 v135, 1.0, v135
	v_exp_f32_e32 v130, v130
	v_exp_f32_e32 v131, v131
	v_rcp_f32_e32 v134, v134
	v_rcp_f32_e32 v135, v135
	v_mul_f32_e32 v132, 0xbfb8aa3b, v132
	v_mul_f32_e32 v133, 0xbfb8aa3b, v133
	v_exp_f32_e32 v132, v132
	v_exp_f32_e32 v133, v133
	v_add_f32_e32 v130, 1.0, v130
	v_add_f32_e32 v131, 1.0, v131
	v_rcp_f32_e32 v130, v130
	v_rcp_f32_e32 v131, v131
	v_add_f32_e32 v132, 1.0, v132
	v_add_f32_e32 v133, 1.0, v133
	v_rcp_f32_e32 v132, v132
	v_rcp_f32_e32 v133, v133
	s_waitcnt vmcnt(0)
	v_fmamk_f32 v198, v198, 0x3a800000, v228
	v_rsq_f32_e32 v204, v198
	v_lshlrev_b32_e32 v212, 16, v202
	v_and_b32_e32 v215, 0xffff0000, v200
	v_and_b32_e32 v213, 0xffff0000, v202
	v_lshlrev_b32_e32 v202, 16, v203
	v_and_b32_e32 v203, 0xffff0000, v203
	v_fmamk_f32 v198, v214, 0x3a800000, v228
	v_lshlrev_b32_e32 v214, 16, v200
	v_lshlrev_b32_e32 v200, 16, v201
	v_and_b32_e32 v201, 0xffff0000, v201
	v_pk_mul_f32 v[200:201], v[204:205], v[200:201] op_sel_hi:[0,1]
	v_pk_mul_f32 v[200:201], v[40:41], v[200:201]
	v_rsq_f32_e32 v198, v198
	v_pk_mul_f32 v[214:215], v[204:205], v[214:215] op_sel_hi:[0,1]
	v_pk_fma_f32 v[136:137], v[200:201], v[136:137], v[202:203]
	v_lshlrev_b64 v[200:201], 12, v[152:153]
	v_pk_mul_f32 v[214:215], v[38:39], v[214:215]
	v_lshl_add_u64 v[200:201], s[54:55], 0, v[200:201]
	v_pk_fma_f32 v[134:135], v[214:215], v[134:135], v[212:213]
	v_lshl_add_u64 v[200:201], v[200:201], 0, v[148:149]
	global_store_dwordx4 v[200:201], v[134:137], off nt
	s_nop 1
	v_lshlrev_b32_e32 v136, 16, v194
	v_and_b32_e32 v137, 0xffff0000, v194
	v_pk_mul_f32 v[136:137], v[198:199], v[136:137] op_sel_hi:[0,1]
	v_lshlrev_b32_e32 v134, 16, v196
	v_and_b32_e32 v135, 0xffff0000, v196
	v_pk_mul_f32 v[136:137], v[38:39], v[136:137]
	s_nop 0
	v_pk_fma_f32 v[130:131], v[136:137], v[130:131], v[134:135]
	v_lshlrev_b32_e32 v136, 16, v195
	v_and_b32_e32 v137, 0xffff0000, v195
	v_pk_mul_f32 v[136:137], v[198:199], v[136:137] op_sel_hi:[0,1]
	v_lshlrev_b32_e32 v134, 16, v197
	v_and_b32_e32 v135, 0xffff0000, v197
	v_pk_mul_f32 v[136:137], v[40:41], v[136:137]
	s_nop 0
	v_pk_fma_f32 v[132:133], v[136:137], v[132:133], v[134:135]
	v_lshlrev_b64 v[134:135], 12, v[184:185]
	v_lshl_add_u64 v[134:135], s[54:55], 0, v[134:135]
	v_lshl_add_u64 v[134:135], v[134:135], 0, v[148:149]
	global_store_dwordx4 v[134:135], v[130:133], off nt
	ds_write_b128 v208, v[126:129]
	ds_write_b128 v208, v[122:125] offset:16
	ds_read_b128 v[122:125], v209
	ds_read_b128 v[126:129], v209 offset:1152
	v_lshlrev_b32_e32 v132, 16, v180
	v_and_b32_e32 v133, 0xffff0000, v180
	v_pk_mul_f32 v[132:133], v[204:205], v[132:133] op_sel_hi:[0,1]
	s_waitcnt lgkmcnt(1)
;     __device__ __forceinline__ void operator()(const f32x4 (&acc)[2][2][4][2], const Unit& u_, int wr, int wc, int fr, int fq) const {
;     ...
;             for (int m = 0; m < 2; ++m) {
;                 const float rstd[2] = {__builtin_amdgcn_rsqf(sq[m][0] * (1.0f / 1024.0f) + 1e-6f), __builtin_amdgcn_rsqf(sq[m][1] * (1.0f / 1024.0f) + 1e-6f)};
; #pragma unroll
;                 for (int bj = 0; bj < 2; ++bj) { f32x4 a[2]; xchg_f32(xl, fr, fq, l, acc[ai][bj][m0 + m][0], acc[ai][bj][m0 + m][1], a[0], a[1]);
; #pragma unroll
;                     for (int t = 0; t < 2; ++t) { const unsigned hw[2] = {hb[m][bj][t].x, hb[m][bj][t].y}, ew[2] = {eb[m][bj][t].x, eb[m][bj][t].y};
;                         f32x4 o;
; #pragma unroll
;                         for (int i = 0; i < 4; ++i) { const float h = (i & 1) ? __uint_as_float(hw[i >> 1] & 0xffff0000u) : __uint_as_float(hw[i >> 1] << 16);
;                             const float ee = (i & 1) ? __uint_as_float(ew[i >> 1] & 0xffff0000u) : __uint_as_float(ew[i >> 1] << 16);
;                             const float sg = __builtin_amdgcn_rcpf(1.0f + __expf(-a[t][i]));
;                             o[i] = h + sg * (ee * rstd[t] * g4[bj][i]); }
;                         *(f32x4*)(y + (size_t)(rowb + ai * HALF + (m0 + m) * 16 + 8 * t) * 1024 + colb + bj * HALF) = o; } } }
	v_mul_f32_e32 v122, 0xbfb8aa3b, v122
	v_mul_f32_e32 v123, 0xbfb8aa3b, v123
	v_exp_f32_e32 v122, v122
	v_exp_f32_e32 v123, v123
	v_mul_f32_e32 v124, 0xbfb8aa3b, v124
	v_mul_f32_e32 v125, 0xbfb8aa3b, v125
	v_exp_f32_e32 v124, v124
	v_exp_f32_e32 v125, v125
	v_add_f32_e32 v122, 1.0, v122
	v_add_f32_e32 v123, 1.0, v123
	v_rcp_f32_e32 v122, v122
	v_rcp_f32_e32 v123, v123
	v_add_f32_e32 v124, 1.0, v124
	v_add_f32_e32 v125, 1.0, v125
	v_lshlrev_b32_e32 v130, 16, v182
	v_and_b32_e32 v131, 0xffff0000, v182
	v_pk_mul_f32 v[132:133], v[26:27], v[132:133]
	v_rcp_f32_e32 v124, v124
	v_rcp_f32_e32 v125, v125
	v_pk_fma_f32 v[122:123], v[132:133], v[122:123], v[130:131]
	v_lshlrev_b32_e32 v132, 16, v181
	v_and_b32_e32 v133, 0xffff0000, v181
	v_pk_mul_f32 v[132:133], v[204:205], v[132:133] op_sel_hi:[0,1]
	v_lshlrev_b32_e32 v130, 16, v183
	v_and_b32_e32 v131, 0xffff0000, v183
	v_pk_mul_f32 v[132:133], v[28:29], v[132:133]
	v_or_b32_e32 v136, 40, v152
	v_pk_fma_f32 v[124:125], v[132:133], v[124:125], v[130:131]
	global_store_dwordx4 v[200:201], v[122:125], off offset:512 nt
	v_ashrrev_i32_e32 v137, 31, v136
	s_waitcnt lgkmcnt(0)
	v_mul_f32_e32 v122, 0xbfb8aa3b, v126
	v_mul_f32_e32 v123, 0xbfb8aa3b, v127
	v_exp_f32_e32 v122, v122
	v_exp_f32_e32 v123, v123
	v_lshlrev_b32_e32 v126, 16, v172
	v_and_b32_e32 v127, 0xffff0000, v172
	v_add_f32_e32 v122, 1.0, v122
	v_add_f32_e32 v123, 1.0, v123
	v_rcp_f32_e32 v122, v122
	v_rcp_f32_e32 v123, v123
	v_pk_mul_f32 v[126:127], v[198:199], v[126:127] op_sel_hi:[0,1]
	v_lshlrev_b32_e32 v124, 16, v174
	v_and_b32_e32 v125, 0xffff0000, v174
	v_pk_mul_f32 v[126:127], v[26:27], v[126:127]
	s_nop 0
	v_pk_fma_f32 v[122:123], v[126:127], v[122:123], v[124:125]
	v_mul_f32_e32 v124, 0xbfb8aa3b, v128
	v_mul_f32_e32 v125, 0xbfb8aa3b, v129
	v_exp_f32_e32 v124, v124
	v_exp_f32_e32 v125, v125
	v_lshlrev_b32_e32 v128, 16, v173
	v_and_b32_e32 v129, 0xffff0000, v173
	v_add_f32_e32 v124, 1.0, v124
	v_add_f32_e32 v125, 1.0, v125
	v_rcp_f32_e32 v124, v124
	v_rcp_f32_e32 v125, v125
	v_pk_mul_f32 v[128:129], v[198:199], v[128:129] op_sel_hi:[0,1]
	v_lshlrev_b32_e32 v126, 16, v175
	v_and_b32_e32 v127, 0xffff0000, v175
	v_pk_mul_f32 v[128:129], v[28:29], v[128:129]
	s_nop 0
	v_pk_fma_f32 v[124:125], v[128:129], v[124:125], v[126:127]
	global_store_dwordx4 v[134:135], v[122:125], off offset:512 nt
	ds_write_b128 v208, v[118:121]
	ds_write_b128 v208, v[114:117] offset:16
	ds_read_b128 v[114:117], v209
	ds_read_b128 v[118:121], v209 offset:1152
	v_fmamk_f32 v122, v210, 0x3a800000, v228
	v_rsq_f32_e32 v124, v122
	v_lshlrev_b32_e32 v128, 16, v168
	s_waitcnt lgkmcnt(1)
	v_mul_f32_e32 v114, 0xbfb8aa3b, v114
	v_mul_f32_e32 v115, 0xbfb8aa3b, v115
	v_exp_f32_e32 v114, v114
	v_exp_f32_e32 v115, v115
	v_mul_f32_e32 v116, 0xbfb8aa3b, v116
	v_mul_f32_e32 v117, 0xbfb8aa3b, v117
	v_exp_f32_e32 v116, v116
	v_exp_f32_e32 v117, v117
	v_add_f32_e32 v114, 1.0, v114
	v_add_f32_e32 v115, 1.0, v115
	v_rcp_f32_e32 v114, v114
	v_rcp_f32_e32 v115, v115
	v_and_b32_e32 v129, 0xffff0000, v168
	v_pk_mul_f32 v[128:129], v[124:125], v[128:129] op_sel_hi:[0,1]
	v_add_f32_e32 v116, 1.0, v116
	v_add_f32_e32 v117, 1.0, v117
	v_lshlrev_b32_e32 v126, 16, v170
	v_and_b32_e32 v127, 0xffff0000, v170
	v_pk_mul_f32 v[128:129], v[38:39], v[128:129]
	v_rcp_f32_e32 v116, v116
	v_rcp_f32_e32 v117, v117
	v_pk_fma_f32 v[114:115], v[128:129], v[114:115], v[126:127]
	v_lshlrev_b32_e32 v128, 16, v169
	v_and_b32_e32 v129, 0xffff0000, v169
	v_pk_mul_f32 v[128:129], v[124:125], v[128:129] op_sel_hi:[0,1]
	v_lshlrev_b32_e32 v126, 16, v171
	v_and_b32_e32 v127, 0xffff0000, v171
	v_pk_mul_f32 v[128:129], v[40:41], v[128:129]
	v_fmamk_f32 v122, v211, 0x3a800000, v228
	v_pk_fma_f32 v[116:117], v[128:129], v[116:117], v[126:127]
	v_lshlrev_b64 v[126:127], 12, v[166:167]
	v_lshl_add_u64 v[126:127], s[54:55], 0, v[126:127]
	v_lshl_add_u64 v[126:127], v[126:127], 0, v[148:149]
	global_store_dwordx4 v[126:127], v[114:117], off nt
	v_rsq_f32_e32 v122, v122
	s_waitcnt lgkmcnt(0)
	v_mul_f32_e32 v114, 0xbfb8aa3b, v118
	v_mul_f32_e32 v115, 0xbfb8aa3b, v119
	v_exp_f32_e32 v114, v114
	v_exp_f32_e32 v115, v115
	v_lshlrev_b32_e32 v118, 16, v176
	v_and_b32_e32 v119, 0xffff0000, v176
	v_add_f32_e32 v114, 1.0, v114
	v_add_f32_e32 v115, 1.0, v115
	v_rcp_f32_e32 v114, v114
	v_rcp_f32_e32 v115, v115
	v_pk_mul_f32 v[118:119], v[122:123], v[118:119] op_sel_hi:[0,1]
	v_lshlrev_b32_e32 v116, 16, v178
	v_and_b32_e32 v117, 0xffff0000, v178
	v_pk_mul_f32 v[118:119], v[38:39], v[118:119]
	s_nop 0
	v_pk_fma_f32 v[114:115], v[118:119], v[114:115], v[116:117]
	v_mul_f32_e32 v116, 0xbfb8aa3b, v120
	v_mul_f32_e32 v117, 0xbfb8aa3b, v121
	v_exp_f32_e32 v116, v116
	v_exp_f32_e32 v117, v117
	v_lshlrev_b32_e32 v120, 16, v177
	v_and_b32_e32 v121, 0xffff0000, v177
	v_add_f32_e32 v116, 1.0, v116
	v_add_f32_e32 v117, 1.0, v117
	v_rcp_f32_e32 v116, v116
	v_rcp_f32_e32 v117, v117
	v_pk_mul_f32 v[120:121], v[122:123], v[120:121] op_sel_hi:[0,1]
	v_lshlrev_b32_e32 v118, 16, v179
	v_and_b32_e32 v119, 0xffff0000, v179
	v_pk_mul_f32 v[120:121], v[40:41], v[120:121]
	s_nop 0
	v_pk_fma_f32 v[116:117], v[120:121], v[116:117], v[118:119]
	v_lshlrev_b64 v[118:119], 12, v[164:165]
	v_lshl_add_u64 v[118:119], s[54:55], 0, v[118:119]
	v_lshl_add_u64 v[118:119], v[118:119], 0, v[148:149]
	global_store_dwordx4 v[118:119], v[114:117], off nt
	ds_write_b128 v208, v[110:113]
	ds_write_b128 v208, v[106:109] offset:16
	ds_read_b128 v[106:109], v209
	ds_read_b128 v[110:113], v209 offset:1152
	v_lshlrev_b32_e32 v116, 16, v156
	v_and_b32_e32 v117, 0xffff0000, v156
	v_pk_mul_f32 v[116:117], v[124:125], v[116:117] op_sel_hi:[0,1]
	s_waitcnt lgkmcnt(1)
;     __device__ __forceinline__ void operator()(const f32x4 (&acc)[2][2][4][2], const Unit& u_, int wr, int wc, int fr, int fq) const {
;     ...
;         for (int am = 0; am < 4; ++am) { const int ai = am >> 1, m0 = (am & 1) * 2;
;             u32x2 hb[2][2][2], eb[2][2][2]; float sq[2][2];
; #pragma unroll
;             for (int m = 0; m < 2; ++m)
; #pragma unroll
;                 for (int t = 0; t < 2; ++t) { const int row = rowb + ai * HALF + (m0 + m) * 16 + 8 * t; const size_t off = (size_t)row * 1024 + colb; sq[m][t] = ssq[row];
; #pragma unroll
;                     for (int bj = 0; bj < 2; ++bj) { hb[m][bj][t] = *(const u32x2*)(h1b + off + bj * HALF); eb[m][bj][t] = *(const u32x2*)(E + off + bj * HALF); } }
;             asm volatile("" ::: "memory");
; #pragma unroll
;             for (int m = 0; m < 2; ++m) {
;                 const float rstd[2] = {__builtin_amdgcn_rsqf(sq[m][0] * (1.0f / 1024.0f) + 1e-6f), __builtin_amdgcn_rsqf(sq[m][1] * (1.0f / 1024.0f) + 1e-6f)};
; #pragma unroll
;                 for (int bj = 0; bj < 2; ++bj) { f32x4 a[2]; xchg_f32(xl, fr, fq, l, acc[ai][bj][m0 + m][0], acc[ai][bj][m0 + m][1], a[0], a[1]);
; #pragma unroll
;                     for (int t = 0; t < 2; ++t) { const unsigned hw[2] = {hb[m][bj][t].x, hb[m][bj][t].y}, ew[2] = {eb[m][bj][t].x, eb[m][bj][t].y};
;                         f32x4 o;
; #pragma unroll
;                         for (int i = 0; i < 4; ++i) { const float h = (i & 1) ? __uint_as_float(hw[i >> 1] & 0xffff0000u) : __uint_as_float(hw[i >> 1] << 16);
;                             const float ee = (i & 1) ? __uint_as_float(ew[i >> 1] & 0xffff0000u) : __uint_as_float(ew[i >> 1] << 16);
;                             const float sg = __builtin_amdgcn_rcpf(1.0f + __expf(-a[t][i]));
;                             o[i] = h + sg * (ee * rstd[t] * g4[bj][i]); }
;                         *(f32x4*)(y + (size_t)(rowb + ai * HALF + (m0 + m) * 16 + 8 * t) * 1024 + colb + bj * HALF) = o; } } }
	v_mul_f32_e32 v106, 0xbfb8aa3b, v106
	v_mul_f32_e32 v107, 0xbfb8aa3b, v107
	v_exp_f32_e32 v106, v106
	v_exp_f32_e32 v107, v107
	v_mul_f32_e32 v108, 0xbfb8aa3b, v108
	v_mul_f32_e32 v109, 0xbfb8aa3b, v109
	v_exp_f32_e32 v108, v108
	v_exp_f32_e32 v109, v109
	v_add_f32_e32 v106, 1.0, v106
	v_add_f32_e32 v107, 1.0, v107
	v_rcp_f32_e32 v106, v106
	v_rcp_f32_e32 v107, v107
	v_add_f32_e32 v108, 1.0, v108
	v_add_f32_e32 v109, 1.0, v109
	v_lshlrev_b32_e32 v114, 16, v158
	v_and_b32_e32 v115, 0xffff0000, v158
	v_pk_mul_f32 v[116:117], v[26:27], v[116:117]
	v_rcp_f32_e32 v108, v108
	v_rcp_f32_e32 v109, v109
	v_pk_fma_f32 v[106:107], v[116:117], v[106:107], v[114:115]
	v_lshlrev_b32_e32 v116, 16, v157
	v_and_b32_e32 v117, 0xffff0000, v157
	v_pk_mul_f32 v[116:117], v[124:125], v[116:117] op_sel_hi:[0,1]
	v_lshlrev_b32_e32 v114, 16, v159
	v_and_b32_e32 v115, 0xffff0000, v159
	v_pk_mul_f32 v[116:117], v[28:29], v[116:117]
	v_or_b32_e32 v158, 32, v152
	v_pk_fma_f32 v[108:109], v[116:117], v[108:109], v[114:115]
	global_store_dwordx4 v[126:127], v[106:109], off offset:512 nt
	v_ashrrev_i32_e32 v159, 31, v158
	v_or_b32_e32 v120, 48, v152
	s_waitcnt lgkmcnt(0)
	v_mul_f32_e32 v106, 0xbfb8aa3b, v110
	v_mul_f32_e32 v107, 0xbfb8aa3b, v111
	v_exp_f32_e32 v106, v106
	v_exp_f32_e32 v107, v107
	v_lshlrev_b32_e32 v110, 16, v162
	v_and_b32_e32 v111, 0xffff0000, v162
	v_add_f32_e32 v106, 1.0, v106
	v_add_f32_e32 v107, 1.0, v107
	v_rcp_f32_e32 v106, v106
	v_rcp_f32_e32 v107, v107
	v_pk_mul_f32 v[110:111], v[122:123], v[110:111] op_sel_hi:[0,1]
	v_lshlrev_b32_e32 v108, 16, v160
	v_and_b32_e32 v109, 0xffff0000, v160
	v_pk_mul_f32 v[110:111], v[26:27], v[110:111]
	v_ashrrev_i32_e32 v121, 31, v120
	v_pk_fma_f32 v[106:107], v[110:111], v[106:107], v[108:109]
	v_mul_f32_e32 v108, 0xbfb8aa3b, v112
	v_mul_f32_e32 v109, 0xbfb8aa3b, v113
	v_exp_f32_e32 v108, v108
	v_exp_f32_e32 v109, v109
	v_lshlrev_b32_e32 v112, 16, v163
	v_and_b32_e32 v113, 0xffff0000, v163
	v_add_f32_e32 v108, 1.0, v108
	v_add_f32_e32 v109, 1.0, v109
	v_rcp_f32_e32 v108, v108
	v_rcp_f32_e32 v109, v109
	v_pk_mul_f32 v[112:113], v[122:123], v[112:113] op_sel_hi:[0,1]
	v_lshlrev_b32_e32 v110, 16, v161
	v_and_b32_e32 v111, 0xffff0000, v161
	v_pk_mul_f32 v[112:113], v[28:29], v[112:113]
	v_or_b32_e32 v114, 56, v152
	v_pk_fma_f32 v[108:109], v[112:113], v[108:109], v[110:111]
	global_store_dwordx4 v[118:119], v[106:109], off offset:512 nt
	v_ashrrev_i32_e32 v115, 31, v114
	s_nop 0
	v_lshl_add_u64 v[108:109], v[158:159], 2, s[20:21]
	global_load_dword v134, v[108:109], off
	v_lshlrev_b64 v[106:107], 10, v[158:159]
	v_lshl_add_u64 v[106:107], v[106:107], 0, v[150:151]
	v_lshlrev_b64 v[106:107], 1, v[106:107]
	v_lshl_add_u64 v[108:109], s[14:15], 0, v[106:107]
	v_lshl_add_u64 v[106:107], s[18:19], 0, v[106:107]
	global_load_dwordx2 v[166:167], v[108:109], off
	global_load_dwordx2 v[164:165], v[106:107], off
	global_load_dwordx2 v[128:129], v[108:109], off offset:256
	global_load_dwordx2 v[126:127], v[106:107], off offset:256
	v_lshl_add_u64 v[108:109], v[136:137], 2, s[20:21]
	v_lshlrev_b64 v[106:107], 10, v[136:137]
	global_load_dword v153, v[108:109], off
	v_lshl_add_u64 v[106:107], v[106:107], 0, v[150:151]
	v_lshlrev_b64 v[106:107], 1, v[106:107]
	v_lshl_add_u64 v[108:109], s[14:15], 0, v[106:107]
	v_lshl_add_u64 v[106:107], s[18:19], 0, v[106:107]
	global_load_dwordx2 v[160:161], v[108:109], off
	global_load_dwordx2 v[162:163], v[106:107], off
	global_load_dwordx2 v[132:133], v[108:109], off offset:256
	global_load_dwordx2 v[130:131], v[106:107], off offset:256
	v_lshl_add_u64 v[108:109], v[120:121], 2, s[20:21]
	global_load_dword v135, v[108:109], off
	v_lshlrev_b64 v[106:107], 10, v[120:121]
	v_lshl_add_u64 v[106:107], v[106:107], 0, v[150:151]
	v_lshlrev_b64 v[106:107], 1, v[106:107]
	v_lshl_add_u64 v[108:109], s[14:15], 0, v[106:107]
	v_lshl_add_u64 v[106:107], s[18:19], 0, v[106:107]
	global_load_dwordx2 v[124:125], v[108:109], off
	global_load_dwordx2 v[122:123], v[106:107], off
	global_load_dwordx2 v[112:113], v[108:109], off offset:256
	global_load_dwordx2 v[110:111], v[106:107], off offset:256
	v_lshlrev_b64 v[106:107], 10, v[114:115]
	v_lshl_add_u64 v[106:107], v[106:107], 0, v[150:151]
	v_lshl_add_u64 v[108:109], v[114:115], 2, s[20:21]
	v_lshlrev_b64 v[106:107], 1, v[106:107]
	global_load_dword v172, v[108:109], off
	v_lshl_add_u64 v[108:109], s[14:15], 0, v[106:107]
	v_lshl_add_u64 v[156:157], s[18:19], 0, v[106:107]
	global_load_dwordx2 v[118:119], v[108:109], off
	global_load_dwordx2 v[116:117], v[156:157], off
	global_load_dwordx2 v[106:107], v[108:109], off offset:256
	s_nop 0
	global_load_dwordx2 v[108:109], v[156:157], off offset:256
	ds_write_b128 v208, v[102:105]
	ds_write_b128 v208, v[98:101] offset:16
	ds_read_b128 v[98:101], v209
	ds_read_b128 v[102:105], v209 offset:1152
	v_lshlrev_b64 v[158:159], 12, v[158:159]
	v_lshl_add_u64 v[158:159], s[54:55], 0, v[158:159]
	v_lshl_add_u64 v[158:159], v[158:159], 0, v[148:149]
	s_waitcnt lgkmcnt(1)
	v_mul_f32_e32 v98, 0xbfb8aa3b, v98
	v_mul_f32_e32 v99, 0xbfb8aa3b, v99
	v_mul_f32_e32 v100, 0xbfb8aa3b, v100
	v_mul_f32_e32 v101, 0xbfb8aa3b, v101
	v_exp_f32_e32 v98, v98
	v_exp_f32_e32 v99, v99
	v_exp_f32_e32 v100, v100
	v_exp_f32_e32 v101, v101
	v_add_f32_e32 v98, 1.0, v98
	v_add_f32_e32 v99, 1.0, v99
	v_add_f32_e32 v100, 1.0, v100
	v_add_f32_e32 v101, 1.0, v101
	v_rcp_f32_e32 v98, v98
	v_rcp_f32_e32 v99, v99
	v_rcp_f32_e32 v100, v100
	v_rcp_f32_e32 v101, v101
	s_waitcnt vmcnt(19)
	v_fmamk_f32 v134, v134, 0x3a800000, v228
	v_rsq_f32_e32 v156, v134
	s_waitcnt vmcnt(18)
	v_lshlrev_b32_e32 v168, 16, v166
	s_waitcnt vmcnt(17)
;     __device__ __forceinline__ void operator()(const f32x4 (&acc)[2][2][4][2], const Unit& u_, int wr, int wc, int fr, int fq) const {
;     ...
;             for (int m = 0; m < 2; ++m) {
;                 const float rstd[2] = {__builtin_amdgcn_rsqf(sq[m][0] * (1.0f / 1024.0f) + 1e-6f), __builtin_amdgcn_rsqf(sq[m][1] * (1.0f / 1024.0f) + 1e-6f)};
; #pragma unroll
;                 for (int bj = 0; bj < 2; ++bj) { f32x4 a[2]; xchg_f32(xl, fr, fq, l, acc[ai][bj][m0 + m][0], acc[ai][bj][m0 + m][1], a[0], a[1]);
; #pragma unroll
;                     for (int t = 0; t < 2; ++t) { const unsigned hw[2] = {hb[m][bj][t].x, hb[m][bj][t].y}, ew[2] = {eb[m][bj][t].x, eb[m][bj][t].y};
;                         f32x4 o;
; #pragma unroll
;                         for (int i = 0; i < 4; ++i) { const float h = (i & 1) ? __uint_as_float(hw[i >> 1] & 0xffff0000u) : __uint_as_float(hw[i >> 1] << 16);
;                             const float ee = (i & 1) ? __uint_as_float(ew[i >> 1] & 0xffff0000u) : __uint_as_float(ew[i >> 1] << 16);
;                             const float sg = __builtin_amdgcn_rcpf(1.0f + __expf(-a[t][i]));
;                             o[i] = h + sg * (ee * rstd[t] * g4[bj][i]); }
;                         *(f32x4*)(y + (size_t)(rowb + ai * HALF + (m0 + m) * 16 + 8 * t) * 1024 + colb + bj * HALF) = o; } } }
	v_lshlrev_b32_e32 v170, 16, v164
	v_and_b32_e32 v171, 0xffff0000, v164
	v_lshlrev_b32_e32 v164, 16, v165
	v_and_b32_e32 v165, 0xffff0000, v165
	v_pk_mul_f32 v[170:171], v[156:157], v[170:171] op_sel_hi:[0,1]
	v_pk_mul_f32 v[164:165], v[156:157], v[164:165] op_sel_hi:[0,1]
	v_and_b32_e32 v169, 0xffff0000, v166
	v_pk_mul_f32 v[170:171], v[38:39], v[170:171]
	v_lshlrev_b32_e32 v166, 16, v167
	v_and_b32_e32 v167, 0xffff0000, v167
	v_pk_mul_f32 v[164:165], v[40:41], v[164:165]
	v_pk_fma_f32 v[98:99], v[170:171], v[98:99], v[168:169]
	v_pk_fma_f32 v[100:101], v[164:165], v[100:101], v[166:167]
	global_store_dwordx4 v[158:159], v[98:101], off nt
	s_waitcnt vmcnt(15)
	v_fmamk_f32 v134, v153, 0x3a800000, v228
	v_rsq_f32_e32 v134, v134
	s_waitcnt lgkmcnt(0)
	v_mul_f32_e32 v98, 0xbfb8aa3b, v102
	v_mul_f32_e32 v99, 0xbfb8aa3b, v103
	v_exp_f32_e32 v98, v98
	v_exp_f32_e32 v99, v99
	s_waitcnt vmcnt(13)
	v_lshlrev_b32_e32 v102, 16, v162
	v_and_b32_e32 v103, 0xffff0000, v162
	v_add_f32_e32 v98, 1.0, v98
	v_add_f32_e32 v99, 1.0, v99
	v_rcp_f32_e32 v98, v98
	v_rcp_f32_e32 v99, v99
	s_waitcnt vmcnt(10)
	v_pk_mul_f32 v[102:103], v[134:135], v[102:103] op_sel_hi:[0,1]
	v_lshlrev_b32_e32 v100, 16, v160
	v_and_b32_e32 v101, 0xffff0000, v160
	v_pk_mul_f32 v[102:103], v[38:39], v[102:103]
	s_nop 0
	v_pk_fma_f32 v[98:99], v[102:103], v[98:99], v[100:101]
	v_mul_f32_e32 v100, 0xbfb8aa3b, v104
	v_mul_f32_e32 v101, 0xbfb8aa3b, v105
	v_exp_f32_e32 v100, v100
	v_exp_f32_e32 v101, v101
	v_lshlrev_b32_e32 v104, 16, v163
	v_and_b32_e32 v105, 0xffff0000, v163
	v_add_f32_e32 v100, 1.0, v100
	v_add_f32_e32 v101, 1.0, v101
	v_rcp_f32_e32 v100, v100
	v_rcp_f32_e32 v101, v101
	v_pk_mul_f32 v[104:105], v[134:135], v[104:105] op_sel_hi:[0,1]
	v_lshlrev_b32_e32 v102, 16, v161
	v_and_b32_e32 v103, 0xffff0000, v161
	v_pk_mul_f32 v[104:105], v[40:41], v[104:105]
	s_nop 0
	v_pk_fma_f32 v[100:101], v[104:105], v[100:101], v[102:103]
	v_lshlrev_b64 v[102:103], 12, v[136:137]
	v_lshl_add_u64 v[102:103], s[54:55], 0, v[102:103]
	v_lshl_add_u64 v[102:103], v[102:103], 0, v[148:149]
	global_store_dwordx4 v[102:103], v[98:101], off nt
	ds_write_b128 v208, v[94:97]
	ds_write_b128 v208, v[90:93] offset:16
	ds_read_b128 v[90:93], v209
	ds_read_b128 v[94:97], v209 offset:1152
	v_lshlrev_b32_e32 v100, 16, v126
	v_and_b32_e32 v101, 0xffff0000, v126
	v_pk_mul_f32 v[100:101], v[156:157], v[100:101] op_sel_hi:[0,1]
	s_waitcnt lgkmcnt(1)
	v_mul_f32_e32 v90, 0xbfb8aa3b, v90
	v_mul_f32_e32 v91, 0xbfb8aa3b, v91
	v_exp_f32_e32 v90, v90
	v_exp_f32_e32 v91, v91
	v_mul_f32_e32 v92, 0xbfb8aa3b, v92
	v_mul_f32_e32 v93, 0xbfb8aa3b, v93
	v_exp_f32_e32 v92, v92
	v_exp_f32_e32 v93, v93
	v_add_f32_e32 v90, 1.0, v90
	v_add_f32_e32 v91, 1.0, v91
	v_rcp_f32_e32 v90, v90
	v_rcp_f32_e32 v91, v91
	v_add_f32_e32 v92, 1.0, v92
	v_add_f32_e32 v93, 1.0, v93
	v_lshlrev_b32_e32 v98, 16, v128
	v_and_b32_e32 v99, 0xffff0000, v128
	v_pk_mul_f32 v[100:101], v[26:27], v[100:101]
	v_rcp_f32_e32 v92, v92
	v_rcp_f32_e32 v93, v93
	v_pk_fma_f32 v[90:91], v[100:101], v[90:91], v[98:99]
	v_lshlrev_b32_e32 v100, 16, v127
	v_and_b32_e32 v101, 0xffff0000, v127
	v_pk_mul_f32 v[100:101], v[156:157], v[100:101] op_sel_hi:[0,1]
	v_lshlrev_b32_e32 v98, 16, v129
	v_and_b32_e32 v99, 0xffff0000, v129
	v_pk_mul_f32 v[100:101], v[28:29], v[100:101]
	s_nop 0
	v_pk_fma_f32 v[92:93], v[100:101], v[92:93], v[98:99]
	global_store_dwordx4 v[158:159], v[90:93], off offset:512 nt
	s_waitcnt lgkmcnt(0)
	s_nop 0
	v_mul_f32_e32 v90, 0xbfb8aa3b, v94
	v_mul_f32_e32 v91, 0xbfb8aa3b, v95
	v_exp_f32_e32 v90, v90
	v_exp_f32_e32 v91, v91
	v_lshlrev_b32_e32 v94, 16, v130
	v_and_b32_e32 v95, 0xffff0000, v130
	v_add_f32_e32 v90, 1.0, v90
	v_add_f32_e32 v91, 1.0, v91
	v_rcp_f32_e32 v90, v90
	v_rcp_f32_e32 v91, v91
	v_pk_mul_f32 v[94:95], v[134:135], v[94:95] op_sel_hi:[0,1]
	v_lshlrev_b32_e32 v92, 16, v132
	v_and_b32_e32 v93, 0xffff0000, v132
	v_pk_mul_f32 v[94:95], v[26:27], v[94:95]
	s_nop 0
	v_pk_fma_f32 v[90:91], v[94:95], v[90:91], v[92:93]
	v_mul_f32_e32 v92, 0xbfb8aa3b, v96
	v_mul_f32_e32 v93, 0xbfb8aa3b, v97
	v_exp_f32_e32 v92, v92
	v_exp_f32_e32 v93, v93
	v_lshlrev_b32_e32 v96, 16, v131
	v_and_b32_e32 v97, 0xffff0000, v131
	v_add_f32_e32 v92, 1.0, v92
	v_add_f32_e32 v93, 1.0, v93
	v_rcp_f32_e32 v92, v92
	v_rcp_f32_e32 v93, v93
	v_pk_mul_f32 v[96:97], v[134:135], v[96:97] op_sel_hi:[0,1]
	v_lshlrev_b32_e32 v94, 16, v133
	v_and_b32_e32 v95, 0xffff0000, v133
	v_pk_mul_f32 v[96:97], v[28:29], v[96:97]
	s_nop 0
	v_pk_fma_f32 v[92:93], v[96:97], v[92:93], v[94:95]
	global_store_dwordx4 v[102:103], v[90:93], off offset:512 nt
	ds_write_b128 v208, v[86:89]
	ds_write_b128 v208, v[82:85] offset:16
	ds_read_b128 v[82:85], v209
	ds_read_b128 v[86:89], v209 offset:1152
	v_fmamk_f32 v90, v135, 0x3a800000, v228
	v_rsq_f32_e32 v92, v90
	s_waitcnt vmcnt(11)
	v_lshlrev_b32_e32 v96, 16, v122
	s_waitcnt lgkmcnt(1)
	v_mul_f32_e32 v82, 0xbfb8aa3b, v82
	v_mul_f32_e32 v83, 0xbfb8aa3b, v83
	v_exp_f32_e32 v82, v82
	v_exp_f32_e32 v83, v83
	v_mul_f32_e32 v84, 0xbfb8aa3b, v84
	v_mul_f32_e32 v85, 0xbfb8aa3b, v85
	v_exp_f32_e32 v84, v84
	v_exp_f32_e32 v85, v85
	v_add_f32_e32 v82, 1.0, v82
	v_add_f32_e32 v83, 1.0, v83
	v_rcp_f32_e32 v82, v82
	v_rcp_f32_e32 v83, v83
	v_and_b32_e32 v97, 0xffff0000, v122
	v_pk_mul_f32 v[96:97], v[92:93], v[96:97] op_sel_hi:[0,1]
	v_add_f32_e32 v84, 1.0, v84
	v_add_f32_e32 v85, 1.0, v85
	v_lshlrev_b32_e32 v94, 16, v124
	v_and_b32_e32 v95, 0xffff0000, v124
	v_pk_mul_f32 v[96:97], v[38:39], v[96:97]
	v_rcp_f32_e32 v84, v84
	v_rcp_f32_e32 v85, v85
	v_pk_fma_f32 v[82:83], v[96:97], v[82:83], v[94:95]
	v_lshlrev_b32_e32 v96, 16, v123
	v_and_b32_e32 v97, 0xffff0000, v123
	v_pk_mul_f32 v[96:97], v[92:93], v[96:97] op_sel_hi:[0,1]
	v_lshlrev_b32_e32 v94, 16, v125
	v_and_b32_e32 v95, 0xffff0000, v125
	v_pk_mul_f32 v[96:97], v[40:41], v[96:97]
	s_waitcnt vmcnt(8)
;     __device__ __forceinline__ void operator()(const f32x4 (&acc)[2][2][4][2], const Unit& u_, int wr, int wc, int fr, int fq) const {
;     ...
;         for (int am = 0; am < 4; ++am) { const int ai = am >> 1, m0 = (am & 1) * 2;
;             u32x2 hb[2][2][2], eb[2][2][2]; float sq[2][2];
; #pragma unroll
;             for (int m = 0; m < 2; ++m)
; #pragma unroll
;                 for (int t = 0; t < 2; ++t) { const int row = rowb + ai * HALF + (m0 + m) * 16 + 8 * t; const size_t off = (size_t)row * 1024 + colb; sq[m][t] = ssq[row];
; #pragma unroll
;                     for (int bj = 0; bj < 2; ++bj) { hb[m][bj][t] = *(const u32x2*)(h1b + off + bj * HALF); eb[m][bj][t] = *(const u32x2*)(E + off + bj * HALF); } }
;             asm volatile("" ::: "memory");
; #pragma unroll
;             for (int m = 0; m < 2; ++m) {
;                 const float rstd[2] = {__builtin_amdgcn_rsqf(sq[m][0] * (1.0f / 1024.0f) + 1e-6f), __builtin_amdgcn_rsqf(sq[m][1] * (1.0f / 1024.0f) + 1e-6f)};
; #pragma unroll
;                 for (int bj = 0; bj < 2; ++bj) { f32x4 a[2]; xchg_f32(xl, fr, fq, l, acc[ai][bj][m0 + m][0], acc[ai][bj][m0 + m][1], a[0], a[1]);
; #pragma unroll
;                     for (int t = 0; t < 2; ++t) { const unsigned hw[2] = {hb[m][bj][t].x, hb[m][bj][t].y}, ew[2] = {eb[m][bj][t].x, eb[m][bj][t].y};
;                         f32x4 o;
; #pragma unroll
;                         for (int i = 0; i < 4; ++i) { const float h = (i & 1) ? __uint_as_float(hw[i >> 1] & 0xffff0000u) : __uint_as_float(hw[i >> 1] << 16);
;                             const float ee = (i & 1) ? __uint_as_float(ew[i >> 1] & 0xffff0000u) : __uint_as_float(ew[i >> 1] << 16);
;                             const float sg = __builtin_amdgcn_rcpf(1.0f + __expf(-a[t][i]));
;                             o[i] = h + sg * (ee * rstd[t] * g4[bj][i]); }
;                         *(f32x4*)(y + (size_t)(rowb + ai * HALF + (m0 + m) * 16 + 8 * t) * 1024 + colb + bj * HALF) = o; } } }
	v_fmamk_f32 v90, v172, 0x3a800000, v228
	v_pk_fma_f32 v[84:85], v[96:97], v[84:85], v[94:95]
	v_lshlrev_b64 v[94:95], 12, v[120:121]
	v_lshl_add_u64 v[94:95], s[54:55], 0, v[94:95]
	v_lshl_add_u64 v[94:95], v[94:95], 0, v[148:149]
	global_store_dwordx4 v[94:95], v[82:85], off nt
	v_rsq_f32_e32 v90, v90
	v_add_u32_e32 v102, 0x88, v152
	s_waitcnt lgkmcnt(0)
	v_mul_f32_e32 v82, 0xbfb8aa3b, v86
	v_mul_f32_e32 v83, 0xbfb8aa3b, v87
	v_exp_f32_e32 v82, v82
	v_exp_f32_e32 v83, v83
	s_waitcnt vmcnt(7)
	v_lshlrev_b32_e32 v86, 16, v116
	v_and_b32_e32 v87, 0xffff0000, v116
	v_add_f32_e32 v82, 1.0, v82
	v_add_f32_e32 v83, 1.0, v83
	v_rcp_f32_e32 v82, v82
	v_rcp_f32_e32 v83, v83
	v_pk_mul_f32 v[86:87], v[90:91], v[86:87] op_sel_hi:[0,1]
	v_lshlrev_b32_e32 v84, 16, v118
	v_and_b32_e32 v85, 0xffff0000, v118
	v_pk_mul_f32 v[86:87], v[38:39], v[86:87]
	v_ashrrev_i32_e32 v103, 31, v102
	v_pk_fma_f32 v[82:83], v[86:87], v[82:83], v[84:85]
	v_mul_f32_e32 v84, 0xbfb8aa3b, v88
	v_mul_f32_e32 v85, 0xbfb8aa3b, v89
	v_exp_f32_e32 v84, v84
	v_exp_f32_e32 v85, v85
	v_lshlrev_b32_e32 v88, 16, v117
	v_and_b32_e32 v89, 0xffff0000, v117
	v_add_f32_e32 v84, 1.0, v84
	v_add_f32_e32 v85, 1.0, v85
	v_rcp_f32_e32 v84, v84
	v_rcp_f32_e32 v85, v85
	v_pk_mul_f32 v[88:89], v[90:91], v[88:89] op_sel_hi:[0,1]
	v_lshlrev_b32_e32 v86, 16, v119
	v_and_b32_e32 v87, 0xffff0000, v119
	v_pk_mul_f32 v[88:89], v[40:41], v[88:89]
	s_nop 0
	v_pk_fma_f32 v[84:85], v[88:89], v[84:85], v[86:87]
	v_lshlrev_b64 v[86:87], 12, v[114:115]
	v_lshl_add_u64 v[86:87], s[54:55], 0, v[86:87]
	v_lshl_add_u64 v[86:87], v[86:87], 0, v[148:149]
	global_store_dwordx4 v[86:87], v[82:85], off nt
	ds_write_b128 v208, v[78:81]
	ds_write_b128 v208, v[74:77] offset:16
	ds_read_b128 v[74:77], v209
	ds_read_b128 v[78:81], v209 offset:1152
	v_lshlrev_b32_e32 v84, 16, v110
	v_and_b32_e32 v85, 0xffff0000, v110
	v_pk_mul_f32 v[84:85], v[92:93], v[84:85] op_sel_hi:[0,1]
	s_waitcnt lgkmcnt(1)
	v_mul_f32_e32 v74, 0xbfb8aa3b, v74
	v_mul_f32_e32 v75, 0xbfb8aa3b, v75
	v_exp_f32_e32 v74, v74
	v_exp_f32_e32 v75, v75
	v_mul_f32_e32 v76, 0xbfb8aa3b, v76
	v_mul_f32_e32 v77, 0xbfb8aa3b, v77
	v_exp_f32_e32 v76, v76
	v_exp_f32_e32 v77, v77
	v_add_f32_e32 v74, 1.0, v74
	v_add_f32_e32 v75, 1.0, v75
	v_rcp_f32_e32 v74, v74
	v_rcp_f32_e32 v75, v75
	v_add_f32_e32 v76, 1.0, v76
	v_add_f32_e32 v77, 1.0, v77
	v_lshlrev_b32_e32 v82, 16, v112
	v_and_b32_e32 v83, 0xffff0000, v112
	v_pk_mul_f32 v[84:85], v[26:27], v[84:85]
	v_rcp_f32_e32 v76, v76
	v_rcp_f32_e32 v77, v77
	v_pk_fma_f32 v[74:75], v[84:85], v[74:75], v[82:83]
	v_lshlrev_b32_e32 v84, 16, v111
	v_and_b32_e32 v85, 0xffff0000, v111
	v_pk_mul_f32 v[84:85], v[92:93], v[84:85] op_sel_hi:[0,1]
	v_lshlrev_b32_e32 v82, 16, v113
	v_and_b32_e32 v83, 0xffff0000, v113
	v_pk_mul_f32 v[84:85], v[28:29], v[84:85]
	v_add_u32_e32 v88, 0x90, v152
	v_pk_fma_f32 v[76:77], v[84:85], v[76:77], v[82:83]
	global_store_dwordx4 v[94:95], v[74:77], off offset:512 nt
	v_ashrrev_i32_e32 v89, 31, v88
	v_add_u32_e32 v82, 0x98, v152
	s_waitcnt lgkmcnt(0)
	v_mul_f32_e32 v74, 0xbfb8aa3b, v78
	v_mul_f32_e32 v75, 0xbfb8aa3b, v79
	v_exp_f32_e32 v74, v74
	v_exp_f32_e32 v75, v75
	s_waitcnt vmcnt(7)
	v_lshlrev_b32_e32 v78, 16, v108
	v_and_b32_e32 v79, 0xffff0000, v108
	v_add_f32_e32 v74, 1.0, v74
	v_add_f32_e32 v75, 1.0, v75
	v_rcp_f32_e32 v74, v74
	v_rcp_f32_e32 v75, v75
	v_pk_mul_f32 v[78:79], v[90:91], v[78:79] op_sel_hi:[0,1]
	v_lshlrev_b32_e32 v76, 16, v106
	v_and_b32_e32 v77, 0xffff0000, v106
	v_pk_mul_f32 v[78:79], v[26:27], v[78:79]
	v_add_u32_e32 v106, 0x80, v152
	v_pk_fma_f32 v[74:75], v[78:79], v[74:75], v[76:77]
	v_mul_f32_e32 v76, 0xbfb8aa3b, v80
	v_mul_f32_e32 v77, 0xbfb8aa3b, v81
	v_exp_f32_e32 v76, v76
	v_exp_f32_e32 v77, v77
	v_lshlrev_b32_e32 v80, 16, v109
	v_and_b32_e32 v81, 0xffff0000, v109
	v_add_f32_e32 v76, 1.0, v76
	v_add_f32_e32 v77, 1.0, v77
	v_rcp_f32_e32 v76, v76
	v_rcp_f32_e32 v77, v77
	v_pk_mul_f32 v[80:81], v[90:91], v[80:81] op_sel_hi:[0,1]
	v_lshlrev_b32_e32 v78, 16, v107
	v_and_b32_e32 v79, 0xffff0000, v107
	v_pk_mul_f32 v[80:81], v[28:29], v[80:81]
	v_ashrrev_i32_e32 v107, 31, v106
	v_pk_fma_f32 v[76:77], v[80:81], v[76:77], v[78:79]
	global_store_dwordx4 v[86:87], v[74:77], off offset:512 nt
	global_load_dword v104, v[154:155], off offset:512
	v_ashrrev_i32_e32 v83, 31, v82
	v_lshlrev_b64 v[74:75], 10, v[106:107]
	v_lshl_add_u64 v[74:75], v[74:75], 0, v[150:151]
	v_lshlrev_b64 v[74:75], 1, v[74:75]
	v_lshl_add_u64 v[76:77], s[14:15], 0, v[74:75]
	v_lshl_add_u64 v[74:75], s[18:19], 0, v[74:75]
	global_load_dwordx2 v[112:113], v[76:77], off
	global_load_dwordx2 v[110:111], v[74:75], off
	global_load_dwordx2 v[96:97], v[76:77], off offset:256
	global_load_dwordx2 v[94:95], v[74:75], off offset:256
	global_load_dword v118, v[154:155], off offset:544
	v_lshlrev_b64 v[74:75], 10, v[102:103]
	v_lshl_add_u64 v[74:75], v[74:75], 0, v[150:151]
	v_lshlrev_b64 v[74:75], 1, v[74:75]
	v_lshl_add_u64 v[76:77], s[14:15], 0, v[74:75]
	v_lshl_add_u64 v[74:75], s[18:19], 0, v[74:75]
	global_load_dwordx2 v[114:115], v[76:77], off
	global_load_dwordx2 v[116:117], v[74:75], off
	global_load_dwordx2 v[100:101], v[76:77], off offset:256
	global_load_dwordx2 v[98:99], v[74:75], off offset:256
	global_load_dword v105, v[154:155], off offset:576
	v_lshlrev_b64 v[74:75], 10, v[88:89]
	v_lshl_add_u64 v[74:75], v[74:75], 0, v[150:151]
	v_lshlrev_b64 v[74:75], 1, v[74:75]
	v_lshl_add_u64 v[76:77], s[14:15], 0, v[74:75]
	v_lshl_add_u64 v[74:75], s[18:19], 0, v[74:75]
	global_load_dwordx2 v[92:93], v[76:77], off
	global_load_dwordx2 v[90:91], v[74:75], off
	global_load_dwordx2 v[80:81], v[76:77], off offset:256
	global_load_dwordx2 v[78:79], v[74:75], off offset:256
	v_lshlrev_b64 v[74:75], 10, v[82:83]
	v_lshl_add_u64 v[74:75], v[74:75], 0, v[150:151]
	v_lshlrev_b64 v[74:75], 1, v[74:75]
	v_lshl_add_u64 v[76:77], s[14:15], 0, v[74:75]
	global_load_dword v122, v[154:155], off offset:608
	v_lshl_add_u64 v[108:109], s[18:19], 0, v[74:75]
	global_load_dwordx2 v[84:85], v[76:77], off
	global_load_dwordx2 v[86:87], v[108:109], off
	global_load_dwordx2 v[74:75], v[76:77], off offset:256
	s_nop 0
	global_load_dwordx2 v[76:77], v[108:109], off offset:256
	ds_write_b128 v208, v[70:73]
	ds_write_b128 v208, v[66:69] offset:16
	ds_read_b128 v[66:69], v209
	ds_read_b128 v[70:73], v209 offset:1152
	v_lshlrev_b64 v[106:107], 12, v[106:107]
	v_lshl_add_u64 v[106:107], s[54:55], 0, v[106:107]
	v_lshl_add_u64 v[106:107], v[106:107], 0, v[148:149]
	s_waitcnt lgkmcnt(1)
;     __device__ __forceinline__ void operator()(const f32x4 (&acc)[2][2][4][2], const Unit& u_, int wr, int wc, int fr, int fq) const {
;     ...
;             for (int m = 0; m < 2; ++m) {
;                 const float rstd[2] = {__builtin_amdgcn_rsqf(sq[m][0] * (1.0f / 1024.0f) + 1e-6f), __builtin_amdgcn_rsqf(sq[m][1] * (1.0f / 1024.0f) + 1e-6f)};
; #pragma unroll
;                 for (int bj = 0; bj < 2; ++bj) { f32x4 a[2]; xchg_f32(xl, fr, fq, l, acc[ai][bj][m0 + m][0], acc[ai][bj][m0 + m][1], a[0], a[1]);
; #pragma unroll
;                     for (int t = 0; t < 2; ++t) { const unsigned hw[2] = {hb[m][bj][t].x, hb[m][bj][t].y}, ew[2] = {eb[m][bj][t].x, eb[m][bj][t].y};
;                         f32x4 o;
; #pragma unroll
;                         for (int i = 0; i < 4; ++i) { const float h = (i & 1) ? __uint_as_float(hw[i >> 1] & 0xffff0000u) : __uint_as_float(hw[i >> 1] << 16);
;                             const float ee = (i & 1) ? __uint_as_float(ew[i >> 1] & 0xffff0000u) : __uint_as_float(ew[i >> 1] << 16);
;                             const float sg = __builtin_amdgcn_rcpf(1.0f + __expf(-a[t][i]));
;                             o[i] = h + sg * (ee * rstd[t] * g4[bj][i]); }
;                         *(f32x4*)(y + (size_t)(rowb + ai * HALF + (m0 + m) * 16 + 8 * t) * 1024 + colb + bj * HALF) = o; } } }
	v_mul_f32_e32 v66, 0xbfb8aa3b, v66
	v_mul_f32_e32 v67, 0xbfb8aa3b, v67
	v_mul_f32_e32 v68, 0xbfb8aa3b, v68
	v_mul_f32_e32 v69, 0xbfb8aa3b, v69
	v_exp_f32_e32 v66, v66
	v_exp_f32_e32 v67, v67
	v_exp_f32_e32 v68, v68
	v_exp_f32_e32 v69, v69
	v_add_f32_e32 v66, 1.0, v66
	v_add_f32_e32 v67, 1.0, v67
	v_add_f32_e32 v68, 1.0, v68
	v_add_f32_e32 v69, 1.0, v69
	v_rcp_f32_e32 v66, v66
	v_rcp_f32_e32 v67, v67
	v_rcp_f32_e32 v68, v68
	v_rcp_f32_e32 v69, v69
	s_waitcnt vmcnt(19)
	v_fmamk_f32 v104, v104, 0x3a800000, v228
	v_rsq_f32_e32 v108, v104
	s_waitcnt vmcnt(18)
	v_and_b32_e32 v119, 0xffff0000, v112
	s_waitcnt vmcnt(17)
	v_lshlrev_b32_e32 v120, 16, v110
	v_and_b32_e32 v121, 0xffff0000, v110
	v_lshlrev_b32_e32 v110, 16, v111
	v_and_b32_e32 v111, 0xffff0000, v111
	v_pk_mul_f32 v[120:121], v[108:109], v[120:121] op_sel_hi:[0,1]
	v_pk_mul_f32 v[110:111], v[108:109], v[110:111] op_sel_hi:[0,1]
	s_waitcnt vmcnt(14)
	v_fmamk_f32 v104, v118, 0x3a800000, v228
	v_lshlrev_b32_e32 v118, 16, v112
	v_pk_mul_f32 v[120:121], v[38:39], v[120:121]
	v_lshlrev_b32_e32 v112, 16, v113
	v_and_b32_e32 v113, 0xffff0000, v113
	v_pk_mul_f32 v[110:111], v[40:41], v[110:111]
	v_pk_fma_f32 v[66:67], v[120:121], v[66:67], v[118:119]
	v_pk_fma_f32 v[68:69], v[110:111], v[68:69], v[112:113]
	global_store_dwordx4 v[106:107], v[66:69], off nt
	v_rsq_f32_e32 v104, v104
	s_waitcnt lgkmcnt(0)
	v_mul_f32_e32 v66, 0xbfb8aa3b, v70
	v_mul_f32_e32 v67, 0xbfb8aa3b, v71
	v_exp_f32_e32 v66, v66
	v_exp_f32_e32 v67, v67
	s_waitcnt vmcnt(13)
	v_lshlrev_b32_e32 v70, 16, v116
	v_and_b32_e32 v71, 0xffff0000, v116
	v_add_f32_e32 v66, 1.0, v66
	v_add_f32_e32 v67, 1.0, v67
	v_rcp_f32_e32 v66, v66
	v_rcp_f32_e32 v67, v67
	s_waitcnt vmcnt(10)
	v_pk_mul_f32 v[70:71], v[104:105], v[70:71] op_sel_hi:[0,1]
	v_lshlrev_b32_e32 v68, 16, v114
	v_and_b32_e32 v69, 0xffff0000, v114
	v_pk_mul_f32 v[70:71], v[38:39], v[70:71]
	s_nop 0
	v_pk_fma_f32 v[66:67], v[70:71], v[66:67], v[68:69]
	v_mul_f32_e32 v68, 0xbfb8aa3b, v72
	v_mul_f32_e32 v69, 0xbfb8aa3b, v73
	v_exp_f32_e32 v68, v68
	v_exp_f32_e32 v69, v69
	v_lshlrev_b32_e32 v72, 16, v117
	v_and_b32_e32 v73, 0xffff0000, v117
	v_add_f32_e32 v68, 1.0, v68
	v_add_f32_e32 v69, 1.0, v69
	v_rcp_f32_e32 v68, v68
	v_rcp_f32_e32 v69, v69
	v_pk_mul_f32 v[72:73], v[104:105], v[72:73] op_sel_hi:[0,1]
	v_lshlrev_b32_e32 v70, 16, v115
	v_and_b32_e32 v71, 0xffff0000, v115
	v_pk_mul_f32 v[72:73], v[40:41], v[72:73]
	s_nop 0
	v_pk_fma_f32 v[68:69], v[72:73], v[68:69], v[70:71]
	v_lshlrev_b64 v[70:71], 12, v[102:103]
	v_lshl_add_u64 v[70:71], s[54:55], 0, v[70:71]
	v_lshl_add_u64 v[70:71], v[70:71], 0, v[148:149]
	global_store_dwordx4 v[70:71], v[66:69], off nt
	ds_write_b128 v208, v[62:65]
	ds_write_b128 v208, v[58:61] offset:16
	ds_read_b128 v[58:61], v209
	ds_read_b128 v[62:65], v209 offset:1152
	v_lshlrev_b32_e32 v68, 16, v94
	v_and_b32_e32 v69, 0xffff0000, v94
	v_pk_mul_f32 v[68:69], v[108:109], v[68:69] op_sel_hi:[0,1]
	s_waitcnt lgkmcnt(1)
	v_mul_f32_e32 v58, 0xbfb8aa3b, v58
	v_mul_f32_e32 v59, 0xbfb8aa3b, v59
	v_exp_f32_e32 v58, v58
	v_exp_f32_e32 v59, v59
	v_mul_f32_e32 v60, 0xbfb8aa3b, v60
	v_mul_f32_e32 v61, 0xbfb8aa3b, v61
	v_exp_f32_e32 v60, v60
	v_exp_f32_e32 v61, v61
	v_add_f32_e32 v58, 1.0, v58
	v_add_f32_e32 v59, 1.0, v59
	v_rcp_f32_e32 v58, v58
	v_rcp_f32_e32 v59, v59
	v_add_f32_e32 v60, 1.0, v60
	v_add_f32_e32 v61, 1.0, v61
	v_lshlrev_b32_e32 v66, 16, v96
	v_and_b32_e32 v67, 0xffff0000, v96
	v_pk_mul_f32 v[68:69], v[26:27], v[68:69]
	v_rcp_f32_e32 v60, v60
	v_rcp_f32_e32 v61, v61
	v_pk_fma_f32 v[58:59], v[68:69], v[58:59], v[66:67]
	v_lshlrev_b32_e32 v68, 16, v95
	v_and_b32_e32 v69, 0xffff0000, v95
	v_pk_mul_f32 v[68:69], v[108:109], v[68:69] op_sel_hi:[0,1]
	v_lshlrev_b32_e32 v66, 16, v97
	v_and_b32_e32 v67, 0xffff0000, v97
	v_pk_mul_f32 v[68:69], v[28:29], v[68:69]
	s_nop 0
	v_pk_fma_f32 v[60:61], v[68:69], v[60:61], v[66:67]
	global_store_dwordx4 v[106:107], v[58:61], off offset:512 nt
	s_waitcnt lgkmcnt(0)
	s_nop 0
	v_mul_f32_e32 v58, 0xbfb8aa3b, v62
	v_mul_f32_e32 v59, 0xbfb8aa3b, v63
	v_exp_f32_e32 v58, v58
	v_exp_f32_e32 v59, v59
	v_lshlrev_b32_e32 v62, 16, v98
	v_and_b32_e32 v63, 0xffff0000, v98
	v_add_f32_e32 v58, 1.0, v58
	v_add_f32_e32 v59, 1.0, v59
	v_rcp_f32_e32 v58, v58
	v_rcp_f32_e32 v59, v59
	v_pk_mul_f32 v[62:63], v[104:105], v[62:63] op_sel_hi:[0,1]
	v_lshlrev_b32_e32 v60, 16, v100
	v_and_b32_e32 v61, 0xffff0000, v100
	v_pk_mul_f32 v[62:63], v[26:27], v[62:63]
	s_nop 0
	v_pk_fma_f32 v[58:59], v[62:63], v[58:59], v[60:61]
	v_mul_f32_e32 v60, 0xbfb8aa3b, v64
	v_mul_f32_e32 v61, 0xbfb8aa3b, v65
	v_exp_f32_e32 v60, v60
	v_exp_f32_e32 v61, v61
	v_lshlrev_b32_e32 v64, 16, v99
	v_and_b32_e32 v65, 0xffff0000, v99
	v_add_f32_e32 v60, 1.0, v60
	v_add_f32_e32 v61, 1.0, v61
	v_rcp_f32_e32 v60, v60
	v_rcp_f32_e32 v61, v61
	v_pk_mul_f32 v[64:65], v[104:105], v[64:65] op_sel_hi:[0,1]
	v_lshlrev_b32_e32 v62, 16, v101
	v_and_b32_e32 v63, 0xffff0000, v101
	v_pk_mul_f32 v[64:65], v[28:29], v[64:65]
	s_nop 0
	v_pk_fma_f32 v[60:61], v[64:65], v[60:61], v[62:63]
	global_store_dwordx4 v[70:71], v[58:61], off offset:512 nt
	ds_write_b128 v208, v[54:57]
	ds_write_b128 v208, v[50:53] offset:16
	ds_read_b128 v[50:53], v209
	ds_read_b128 v[54:57], v209 offset:1152
	v_fmamk_f32 v58, v105, 0x3a800000, v228
	v_rsq_f32_e32 v60, v58
	s_waitcnt vmcnt(11)
	v_lshlrev_b32_e32 v64, 16, v90
	s_waitcnt lgkmcnt(1)
;     __device__ __forceinline__ void operator()(const f32x4 (&acc)[2][2][4][2], const Unit& u_, int wr, int wc, int fr, int fq) const {
;     ...
;                 for (int t = 0; t < 2; ++t) { const int row = rowb + ai * HALF + (m0 + m) * 16 + 8 * t; const size_t off = (size_t)row * 1024 + colb; sq[m][t] = ssq[row];
; #pragma unroll
;                     for (int bj = 0; bj < 2; ++bj) { hb[m][bj][t] = *(const u32x2*)(h1b + off + bj * HALF); eb[m][bj][t] = *(const u32x2*)(E + off + bj * HALF); } }
;             asm volatile("" ::: "memory");
; #pragma unroll
;             for (int m = 0; m < 2; ++m) {
;                 const float rstd[2] = {__builtin_amdgcn_rsqf(sq[m][0] * (1.0f / 1024.0f) + 1e-6f), __builtin_amdgcn_rsqf(sq[m][1] * (1.0f / 1024.0f) + 1e-6f)};
; #pragma unroll
;                 for (int bj = 0; bj < 2; ++bj) { f32x4 a[2]; xchg_f32(xl, fr, fq, l, acc[ai][bj][m0 + m][0], acc[ai][bj][m0 + m][1], a[0], a[1]);
; #pragma unroll
;                     for (int t = 0; t < 2; ++t) { const unsigned hw[2] = {hb[m][bj][t].x, hb[m][bj][t].y}, ew[2] = {eb[m][bj][t].x, eb[m][bj][t].y};
;                         f32x4 o;
; #pragma unroll
;                         for (int i = 0; i < 4; ++i) { const float h = (i & 1) ? __uint_as_float(hw[i >> 1] & 0xffff0000u) : __uint_as_float(hw[i >> 1] << 16);
;                             const float ee = (i & 1) ? __uint_as_float(ew[i >> 1] & 0xffff0000u) : __uint_as_float(ew[i >> 1] << 16);
;                             const float sg = __builtin_amdgcn_rcpf(1.0f + __expf(-a[t][i]));
;                             o[i] = h + sg * (ee * rstd[t] * g4[bj][i]); }
;                         *(f32x4*)(y + (size_t)(rowb + ai * HALF + (m0 + m) * 16 + 8 * t) * 1024 + colb + bj * HALF) = o; } } }
	v_mul_f32_e32 v50, 0xbfb8aa3b, v50
	v_mul_f32_e32 v51, 0xbfb8aa3b, v51
	v_exp_f32_e32 v50, v50
	v_exp_f32_e32 v51, v51
	v_mul_f32_e32 v52, 0xbfb8aa3b, v52
	v_mul_f32_e32 v53, 0xbfb8aa3b, v53
	v_exp_f32_e32 v52, v52
	v_exp_f32_e32 v53, v53
	v_add_f32_e32 v50, 1.0, v50
	v_add_f32_e32 v51, 1.0, v51
	v_rcp_f32_e32 v50, v50
	v_rcp_f32_e32 v51, v51
	v_and_b32_e32 v65, 0xffff0000, v90
	v_pk_mul_f32 v[64:65], v[60:61], v[64:65] op_sel_hi:[0,1]
	v_add_f32_e32 v52, 1.0, v52
	v_add_f32_e32 v53, 1.0, v53
	v_lshlrev_b32_e32 v62, 16, v92
	v_and_b32_e32 v63, 0xffff0000, v92
	v_pk_mul_f32 v[64:65], v[38:39], v[64:65]
	v_rcp_f32_e32 v52, v52
	v_rcp_f32_e32 v53, v53
	v_pk_fma_f32 v[50:51], v[64:65], v[50:51], v[62:63]
	v_lshlrev_b32_e32 v64, 16, v91
	v_and_b32_e32 v65, 0xffff0000, v91
	v_pk_mul_f32 v[64:65], v[60:61], v[64:65] op_sel_hi:[0,1]
	v_lshlrev_b32_e32 v62, 16, v93
	v_and_b32_e32 v63, 0xffff0000, v93
	v_pk_mul_f32 v[64:65], v[40:41], v[64:65]
	s_waitcnt vmcnt(8)
	v_fmamk_f32 v58, v122, 0x3a800000, v228
	v_pk_fma_f32 v[52:53], v[64:65], v[52:53], v[62:63]
	v_lshlrev_b64 v[62:63], 12, v[88:89]
	v_lshl_add_u64 v[62:63], s[54:55], 0, v[62:63]
	v_lshl_add_u64 v[62:63], v[62:63], 0, v[148:149]
	global_store_dwordx4 v[62:63], v[50:53], off nt
	v_rsq_f32_e32 v58, v58
	v_add_u32_e32 v70, 0xa8, v152
	s_waitcnt lgkmcnt(0)
	v_mul_f32_e32 v50, 0xbfb8aa3b, v54
	v_mul_f32_e32 v51, 0xbfb8aa3b, v55
	v_exp_f32_e32 v50, v50
	v_exp_f32_e32 v51, v51
	s_waitcnt vmcnt(7)
	v_lshlrev_b32_e32 v54, 16, v86
	v_and_b32_e32 v55, 0xffff0000, v86
	v_add_f32_e32 v50, 1.0, v50
	v_add_f32_e32 v51, 1.0, v51
	v_rcp_f32_e32 v50, v50
	v_rcp_f32_e32 v51, v51
	v_pk_mul_f32 v[54:55], v[58:59], v[54:55] op_sel_hi:[0,1]
	v_lshlrev_b32_e32 v52, 16, v84
	v_and_b32_e32 v53, 0xffff0000, v84
	v_pk_mul_f32 v[54:55], v[38:39], v[54:55]
	v_ashrrev_i32_e32 v71, 31, v70
	v_pk_fma_f32 v[50:51], v[54:55], v[50:51], v[52:53]
	v_mul_f32_e32 v52, 0xbfb8aa3b, v56
	v_mul_f32_e32 v53, 0xbfb8aa3b, v57
	v_exp_f32_e32 v52, v52
	v_exp_f32_e32 v53, v53
	v_lshlrev_b32_e32 v56, 16, v87
	v_and_b32_e32 v57, 0xffff0000, v87
	v_add_f32_e32 v52, 1.0, v52
	v_add_f32_e32 v53, 1.0, v53
	v_rcp_f32_e32 v52, v52
	v_rcp_f32_e32 v53, v53
	v_pk_mul_f32 v[56:57], v[58:59], v[56:57] op_sel_hi:[0,1]
	v_lshlrev_b32_e32 v54, 16, v85
	v_and_b32_e32 v55, 0xffff0000, v85
	v_pk_mul_f32 v[56:57], v[40:41], v[56:57]
	s_nop 0
	v_pk_fma_f32 v[52:53], v[56:57], v[52:53], v[54:55]
	v_lshlrev_b64 v[54:55], 12, v[82:83]
	v_lshl_add_u64 v[54:55], s[54:55], 0, v[54:55]
	v_lshl_add_u64 v[54:55], v[54:55], 0, v[148:149]
	global_store_dwordx4 v[54:55], v[50:53], off nt
	ds_write_b128 v208, v[46:49]
	ds_write_b128 v208, v[42:45] offset:16
	ds_read_b128 v[42:45], v209
	ds_read_b128 v[46:49], v209 offset:1152
	v_lshlrev_b32_e32 v52, 16, v78
	v_and_b32_e32 v53, 0xffff0000, v78
	v_pk_mul_f32 v[52:53], v[60:61], v[52:53] op_sel_hi:[0,1]
	s_waitcnt lgkmcnt(1)
	v_mul_f32_e32 v42, 0xbfb8aa3b, v42
	v_mul_f32_e32 v43, 0xbfb8aa3b, v43
	v_exp_f32_e32 v42, v42
	v_exp_f32_e32 v43, v43
	v_mul_f32_e32 v44, 0xbfb8aa3b, v44
	v_mul_f32_e32 v45, 0xbfb8aa3b, v45
	v_exp_f32_e32 v44, v44
	v_exp_f32_e32 v45, v45
	v_add_f32_e32 v42, 1.0, v42
	v_add_f32_e32 v43, 1.0, v43
	v_rcp_f32_e32 v42, v42
	v_rcp_f32_e32 v43, v43
	v_add_f32_e32 v44, 1.0, v44
	v_add_f32_e32 v45, 1.0, v45
	v_lshlrev_b32_e32 v50, 16, v80
	v_and_b32_e32 v51, 0xffff0000, v80
	v_pk_mul_f32 v[52:53], v[26:27], v[52:53]
	v_rcp_f32_e32 v44, v44
	v_rcp_f32_e32 v45, v45
	v_pk_fma_f32 v[42:43], v[52:53], v[42:43], v[50:51]
	v_lshlrev_b32_e32 v52, 16, v79
	v_and_b32_e32 v53, 0xffff0000, v79
	v_pk_mul_f32 v[52:53], v[60:61], v[52:53] op_sel_hi:[0,1]
	v_lshlrev_b32_e32 v50, 16, v81
	v_and_b32_e32 v51, 0xffff0000, v81
	v_pk_mul_f32 v[52:53], v[28:29], v[52:53]
	v_add_u32_e32 v56, 0xb0, v152
	v_pk_fma_f32 v[44:45], v[52:53], v[44:45], v[50:51]
	global_store_dwordx4 v[62:63], v[42:45], off offset:512 nt
	v_ashrrev_i32_e32 v57, 31, v56
	v_add_u32_e32 v50, 0xb8, v152
	s_waitcnt lgkmcnt(0)
	v_mul_f32_e32 v42, 0xbfb8aa3b, v46
	v_mul_f32_e32 v43, 0xbfb8aa3b, v47
	v_exp_f32_e32 v42, v42
	v_exp_f32_e32 v43, v43
	s_waitcnt vmcnt(7)
	v_lshlrev_b32_e32 v46, 16, v76
	v_and_b32_e32 v47, 0xffff0000, v76
	v_add_f32_e32 v42, 1.0, v42
	v_add_f32_e32 v43, 1.0, v43
	v_rcp_f32_e32 v42, v42
	v_rcp_f32_e32 v43, v43
	v_pk_mul_f32 v[46:47], v[58:59], v[46:47] op_sel_hi:[0,1]
	v_lshlrev_b32_e32 v44, 16, v74
	v_and_b32_e32 v45, 0xffff0000, v74
	v_pk_mul_f32 v[46:47], v[26:27], v[46:47]
	v_add_u32_e32 v74, 0xa0, v152
	v_pk_fma_f32 v[42:43], v[46:47], v[42:43], v[44:45]
	v_mul_f32_e32 v44, 0xbfb8aa3b, v48
	v_mul_f32_e32 v45, 0xbfb8aa3b, v49
	v_exp_f32_e32 v44, v44
	v_exp_f32_e32 v45, v45
	v_lshlrev_b32_e32 v48, 16, v77
	v_and_b32_e32 v49, 0xffff0000, v77
	v_add_f32_e32 v44, 1.0, v44
	v_add_f32_e32 v45, 1.0, v45
	v_rcp_f32_e32 v44, v44
	v_rcp_f32_e32 v45, v45
	v_pk_mul_f32 v[48:49], v[58:59], v[48:49] op_sel_hi:[0,1]
	v_lshlrev_b32_e32 v46, 16, v75
	v_and_b32_e32 v47, 0xffff0000, v75
	v_pk_mul_f32 v[48:49], v[28:29], v[48:49]
	v_ashrrev_i32_e32 v75, 31, v74
	v_pk_fma_f32 v[44:45], v[48:49], v[44:45], v[46:47]
	global_store_dwordx4 v[54:55], v[42:45], off offset:512 nt
	global_load_dword v72, v[154:155], off offset:640
	v_ashrrev_i32_e32 v51, 31, v50
	v_lshlrev_b64 v[42:43], 10, v[74:75]
	v_lshl_add_u64 v[42:43], v[42:43], 0, v[150:151]
	v_lshlrev_b64 v[42:43], 1, v[42:43]
	v_lshl_add_u64 v[44:45], s[14:15], 0, v[42:43]
	v_lshl_add_u64 v[42:43], s[18:19], 0, v[42:43]
	global_load_dwordx2 v[80:81], v[44:45], off
	global_load_dwordx2 v[78:79], v[42:43], off
	global_load_dwordx2 v[64:65], v[44:45], off offset:256
	global_load_dwordx2 v[62:63], v[42:43], off offset:256
;     __device__ __forceinline__ void operator()(const f32x4 (&acc)[2][2][4][2], const Unit& u_, int wr, int wc, int fr, int fq) const {
;     ...
;                 for (int t = 0; t < 2; ++t) { const int row = rowb + ai * HALF + (m0 + m) * 16 + 8 * t; const size_t off = (size_t)row * 1024 + colb; sq[m][t] = ssq[row];
; #pragma unroll
;                     for (int bj = 0; bj < 2; ++bj) { hb[m][bj][t] = *(const u32x2*)(h1b + off + bj * HALF); eb[m][bj][t] = *(const u32x2*)(E + off + bj * HALF); } }
;             asm volatile("" ::: "memory");
; #pragma unroll
;             for (int m = 0; m < 2; ++m) {
;                 const float rstd[2] = {__builtin_amdgcn_rsqf(sq[m][0] * (1.0f / 1024.0f) + 1e-6f), __builtin_amdgcn_rsqf(sq[m][1] * (1.0f / 1024.0f) + 1e-6f)};
; #pragma unroll
;                 for (int bj = 0; bj < 2; ++bj) { f32x4 a[2]; xchg_f32(xl, fr, fq, l, acc[ai][bj][m0 + m][0], acc[ai][bj][m0 + m][1], a[0], a[1]);
; #pragma unroll
;                     for (int t = 0; t < 2; ++t) { const unsigned hw[2] = {hb[m][bj][t].x, hb[m][bj][t].y}, ew[2] = {eb[m][bj][t].x, eb[m][bj][t].y};
;                         f32x4 o;
; #pragma unroll
;                         for (int i = 0; i < 4; ++i) { const float h = (i & 1) ? __uint_as_float(hw[i >> 1] & 0xffff0000u) : __uint_as_float(hw[i >> 1] << 16);
;                             const float ee = (i & 1) ? __uint_as_float(ew[i >> 1] & 0xffff0000u) : __uint_as_float(ew[i >> 1] << 16);
;                             const float sg = __builtin_amdgcn_rcpf(1.0f + __expf(-a[t][i]));
;                             o[i] = h + sg * (ee * rstd[t] * g4[bj][i]); }
;                         *(f32x4*)(y + (size_t)(rowb + ai * HALF + (m0 + m) * 16 + 8 * t) * 1024 + colb + bj * HALF) = o; } } }
	global_load_dword v86, v[154:155], off offset:672
	v_lshlrev_b64 v[42:43], 10, v[70:71]
	v_lshl_add_u64 v[42:43], v[42:43], 0, v[150:151]
	v_lshlrev_b64 v[42:43], 1, v[42:43]
	v_lshl_add_u64 v[44:45], s[14:15], 0, v[42:43]
	v_lshl_add_u64 v[42:43], s[18:19], 0, v[42:43]
	global_load_dwordx2 v[82:83], v[44:45], off
	global_load_dwordx2 v[84:85], v[42:43], off
	global_load_dwordx2 v[68:69], v[44:45], off offset:256
	global_load_dwordx2 v[66:67], v[42:43], off offset:256
	global_load_dword v73, v[154:155], off offset:704
	v_lshlrev_b64 v[42:43], 10, v[56:57]
	v_lshl_add_u64 v[42:43], v[42:43], 0, v[150:151]
	v_lshlrev_b64 v[42:43], 1, v[42:43]
	v_lshl_add_u64 v[44:45], s[14:15], 0, v[42:43]
	v_lshl_add_u64 v[42:43], s[18:19], 0, v[42:43]
	global_load_dwordx2 v[60:61], v[44:45], off
	global_load_dwordx2 v[58:59], v[42:43], off
	global_load_dwordx2 v[48:49], v[44:45], off offset:256
	global_load_dwordx2 v[46:47], v[42:43], off offset:256
	v_lshlrev_b64 v[42:43], 10, v[50:51]
	v_lshl_add_u64 v[42:43], v[42:43], 0, v[150:151]
	v_lshlrev_b64 v[42:43], 1, v[42:43]
	v_lshl_add_u64 v[44:45], s[14:15], 0, v[42:43]
	global_load_dword v90, v[154:155], off offset:736
	v_lshl_add_u64 v[76:77], s[18:19], 0, v[42:43]
	global_load_dwordx2 v[52:53], v[44:45], off
	global_load_dwordx2 v[54:55], v[76:77], off
	global_load_dwordx2 v[42:43], v[44:45], off offset:256
	s_nop 0
	global_load_dwordx2 v[44:45], v[76:77], off offset:256
	ds_write_b128 v208, v[34:37]
	ds_write_b128 v208, v[30:33] offset:16
	ds_read_b128 v[30:33], v209
	ds_read_b128 v[34:37], v209 offset:1152
	v_lshlrev_b64 v[74:75], 12, v[74:75]
	v_lshl_add_u64 v[74:75], s[54:55], 0, v[74:75]
	v_lshl_add_u64 v[74:75], v[74:75], 0, v[148:149]
	s_waitcnt lgkmcnt(1)
	v_mul_f32_e32 v30, 0xbfb8aa3b, v30
	v_mul_f32_e32 v31, 0xbfb8aa3b, v31
	v_mul_f32_e32 v32, 0xbfb8aa3b, v32
	v_mul_f32_e32 v33, 0xbfb8aa3b, v33
	v_exp_f32_e32 v30, v30
	v_exp_f32_e32 v31, v31
	v_exp_f32_e32 v32, v32
	v_exp_f32_e32 v33, v33
	v_add_f32_e32 v30, 1.0, v30
	v_add_f32_e32 v31, 1.0, v31
	v_add_f32_e32 v32, 1.0, v32
	v_add_f32_e32 v33, 1.0, v33
	v_rcp_f32_e32 v30, v30
	v_rcp_f32_e32 v31, v31
	v_rcp_f32_e32 v32, v32
	v_rcp_f32_e32 v33, v33
	s_waitcnt vmcnt(19)
	v_fmamk_f32 v72, v72, 0x3a800000, v228
	v_rsq_f32_e32 v76, v72
	s_waitcnt vmcnt(18)
	v_and_b32_e32 v87, 0xffff0000, v80
	s_waitcnt vmcnt(17)
	v_lshlrev_b32_e32 v88, 16, v78
	v_and_b32_e32 v89, 0xffff0000, v78
	v_lshlrev_b32_e32 v78, 16, v79
	v_and_b32_e32 v79, 0xffff0000, v79
	v_pk_mul_f32 v[88:89], v[76:77], v[88:89] op_sel_hi:[0,1]
	v_pk_mul_f32 v[78:79], v[76:77], v[78:79] op_sel_hi:[0,1]
	s_waitcnt vmcnt(14)
	v_fmamk_f32 v72, v86, 0x3a800000, v228
	v_lshlrev_b32_e32 v86, 16, v80
	v_pk_mul_f32 v[88:89], v[38:39], v[88:89]
	v_lshlrev_b32_e32 v80, 16, v81
	v_and_b32_e32 v81, 0xffff0000, v81
	v_pk_mul_f32 v[78:79], v[40:41], v[78:79]
	v_pk_fma_f32 v[30:31], v[88:89], v[30:31], v[86:87]
	v_pk_fma_f32 v[32:33], v[78:79], v[32:33], v[80:81]
	global_store_dwordx4 v[74:75], v[30:33], off nt
	v_rsq_f32_e32 v72, v72
	s_waitcnt lgkmcnt(0)
	v_mul_f32_e32 v30, 0xbfb8aa3b, v34
	v_mul_f32_e32 v31, 0xbfb8aa3b, v35
	v_exp_f32_e32 v30, v30
	v_exp_f32_e32 v31, v31
	s_waitcnt vmcnt(13)
	v_lshlrev_b32_e32 v34, 16, v84
	v_and_b32_e32 v35, 0xffff0000, v84
	v_add_f32_e32 v30, 1.0, v30
	v_add_f32_e32 v31, 1.0, v31
	v_rcp_f32_e32 v30, v30
	v_rcp_f32_e32 v31, v31
	s_waitcnt vmcnt(10)
	v_pk_mul_f32 v[34:35], v[72:73], v[34:35] op_sel_hi:[0,1]
	v_lshlrev_b32_e32 v32, 16, v82
	v_and_b32_e32 v33, 0xffff0000, v82
	v_pk_mul_f32 v[34:35], v[38:39], v[34:35]
	s_nop 0
	v_pk_fma_f32 v[30:31], v[34:35], v[30:31], v[32:33]
	v_mul_f32_e32 v32, 0xbfb8aa3b, v36
	v_mul_f32_e32 v33, 0xbfb8aa3b, v37
	v_exp_f32_e32 v32, v32
	v_exp_f32_e32 v33, v33
	v_lshlrev_b32_e32 v36, 16, v85
	v_and_b32_e32 v37, 0xffff0000, v85
	v_add_f32_e32 v32, 1.0, v32
	v_add_f32_e32 v33, 1.0, v33
	v_rcp_f32_e32 v32, v32
	v_rcp_f32_e32 v33, v33
	v_pk_mul_f32 v[36:37], v[72:73], v[36:37] op_sel_hi:[0,1]
	v_lshlrev_b32_e32 v34, 16, v83
	v_and_b32_e32 v35, 0xffff0000, v83
	v_pk_mul_f32 v[36:37], v[40:41], v[36:37]
	s_nop 0
	v_pk_fma_f32 v[32:33], v[36:37], v[32:33], v[34:35]
	v_lshlrev_b64 v[34:35], 12, v[70:71]
	v_lshl_add_u64 v[34:35], s[54:55], 0, v[34:35]
	v_lshl_add_u64 v[34:35], v[34:35], 0, v[148:149]
	global_store_dwordx4 v[34:35], v[30:33], off nt
	ds_write_b128 v208, v[22:25]
	ds_write_b128 v208, v[18:21] offset:16
	ds_read_b128 v[18:21], v209
	ds_read_b128 v[22:25], v209 offset:1152
	v_lshlrev_b32_e32 v32, 16, v62
	v_and_b32_e32 v33, 0xffff0000, v62
	v_pk_mul_f32 v[32:33], v[76:77], v[32:33] op_sel_hi:[0,1]
	s_waitcnt lgkmcnt(1)
	v_mul_f32_e32 v18, 0xbfb8aa3b, v18
	v_mul_f32_e32 v19, 0xbfb8aa3b, v19
	v_exp_f32_e32 v18, v18
	v_exp_f32_e32 v19, v19
	v_mul_f32_e32 v20, 0xbfb8aa3b, v20
	v_mul_f32_e32 v21, 0xbfb8aa3b, v21
	v_exp_f32_e32 v20, v20
	v_exp_f32_e32 v21, v21
	v_add_f32_e32 v18, 1.0, v18
	v_add_f32_e32 v19, 1.0, v19
	v_rcp_f32_e32 v18, v18
	v_rcp_f32_e32 v19, v19
	v_add_f32_e32 v20, 1.0, v20
	v_add_f32_e32 v21, 1.0, v21
	v_lshlrev_b32_e32 v30, 16, v64
	v_and_b32_e32 v31, 0xffff0000, v64
	v_pk_mul_f32 v[32:33], v[26:27], v[32:33]
	v_rcp_f32_e32 v20, v20
	v_rcp_f32_e32 v21, v21
	v_pk_fma_f32 v[18:19], v[32:33], v[18:19], v[30:31]
	v_lshlrev_b32_e32 v32, 16, v63
	v_and_b32_e32 v33, 0xffff0000, v63
	v_pk_mul_f32 v[32:33], v[76:77], v[32:33] op_sel_hi:[0,1]
	v_lshlrev_b32_e32 v30, 16, v65
	v_and_b32_e32 v31, 0xffff0000, v65
	v_pk_mul_f32 v[32:33], v[28:29], v[32:33]
	s_nop 0
	v_pk_fma_f32 v[20:21], v[32:33], v[20:21], v[30:31]
	global_store_dwordx4 v[74:75], v[18:21], off offset:512 nt
	s_waitcnt lgkmcnt(0)
; #define PG8_BAR __builtin_amdgcn_s_barrier()
;     __device__ __forceinline__ void operator()(const f32x4 (&acc)[2][2][4][2], const Unit& u_, int wr, int wc, int fr, int fq) const {
;     ...
;                 for (int t = 0; t < 2; ++t) { const int row = rowb + ai * HALF + (m0 + m) * 16 + 8 * t; const size_t off = (size_t)row * 1024 + colb; sq[m][t] = ssq[row];
; #pragma unroll
;                     for (int bj = 0; bj < 2; ++bj) { hb[m][bj][t] = *(const u32x2*)(h1b + off + bj * HALF); eb[m][bj][t] = *(const u32x2*)(E + off + bj * HALF); } }
;             asm volatile("" ::: "memory");
; #pragma unroll
;             for (int m = 0; m < 2; ++m) {
;                 const float rstd[2] = {__builtin_amdgcn_rsqf(sq[m][0] * (1.0f / 1024.0f) + 1e-6f), __builtin_amdgcn_rsqf(sq[m][1] * (1.0f / 1024.0f) + 1e-6f)};
; #pragma unroll
;                 for (int bj = 0; bj < 2; ++bj) { f32x4 a[2]; xchg_f32(xl, fr, fq, l, acc[ai][bj][m0 + m][0], acc[ai][bj][m0 + m][1], a[0], a[1]);
; #pragma unroll
;                     for (int t = 0; t < 2; ++t) { const unsigned hw[2] = {hb[m][bj][t].x, hb[m][bj][t].y}, ew[2] = {eb[m][bj][t].x, eb[m][bj][t].y};
;                         f32x4 o;
; #pragma unroll
;                         for (int i = 0; i < 4; ++i) { const float h = (i & 1) ? __uint_as_float(hw[i >> 1] & 0xffff0000u) : __uint_as_float(hw[i >> 1] << 16);
;                             const float ee = (i & 1) ? __uint_as_float(ew[i >> 1] & 0xffff0000u) : __uint_as_float(ew[i >> 1] << 16);
;                             const float sg = __builtin_amdgcn_rcpf(1.0f + __expf(-a[t][i]));
;                             o[i] = h + sg * (ee * rstd[t] * g4[bj][i]); }
;                         *(f32x4*)(y + (size_t)(rowb + ai * HALF + (m0 + m) * 16 + 8 * t) * 1024 + colb + bj * HALF) = o; } } }
; template <class Epi, class Sched, bool ALIGN_EPI = false, bool SP2 = false>
; __device__ __forceinline__ void gemm_phase(PG8_LAS unsigned char* lds, const Gemm g, const Sched& S, const Epi& E) {
;     ...
;         if constexpr (ALIGN_EPI) { if (wr == 1) PG8_BAR; }
	s_nop 0
	v_mul_f32_e32 v18, 0xbfb8aa3b, v22
	v_mul_f32_e32 v19, 0xbfb8aa3b, v23
	v_exp_f32_e32 v18, v18
	v_exp_f32_e32 v19, v19
	v_lshlrev_b32_e32 v22, 16, v66
	v_and_b32_e32 v23, 0xffff0000, v66
	v_add_f32_e32 v18, 1.0, v18
	v_add_f32_e32 v19, 1.0, v19
	v_rcp_f32_e32 v18, v18
	v_rcp_f32_e32 v19, v19
	v_pk_mul_f32 v[22:23], v[72:73], v[22:23] op_sel_hi:[0,1]
	v_lshlrev_b32_e32 v20, 16, v68
	v_and_b32_e32 v21, 0xffff0000, v68
	v_pk_mul_f32 v[22:23], v[26:27], v[22:23]
	s_nop 0
	v_pk_fma_f32 v[18:19], v[22:23], v[18:19], v[20:21]
	v_mul_f32_e32 v20, 0xbfb8aa3b, v24
	v_mul_f32_e32 v21, 0xbfb8aa3b, v25
	v_exp_f32_e32 v20, v20
	v_exp_f32_e32 v21, v21
	v_lshlrev_b32_e32 v24, 16, v67
	v_and_b32_e32 v25, 0xffff0000, v67
	v_add_f32_e32 v20, 1.0, v20
	v_add_f32_e32 v21, 1.0, v21
	v_rcp_f32_e32 v20, v20
	v_rcp_f32_e32 v21, v21
	v_pk_mul_f32 v[24:25], v[72:73], v[24:25] op_sel_hi:[0,1]
	v_lshlrev_b32_e32 v22, 16, v69
	v_and_b32_e32 v23, 0xffff0000, v69
	v_pk_mul_f32 v[24:25], v[28:29], v[24:25]
	s_nop 0
	v_pk_fma_f32 v[20:21], v[24:25], v[20:21], v[22:23]
	global_store_dwordx4 v[34:35], v[18:21], off offset:512 nt
	ds_write_b128 v208, v[14:17]
	ds_write_b128 v208, v[10:13] offset:16
	ds_read_b128 v[10:13], v209
	ds_read_b128 v[14:17], v209 offset:1152
	v_fmamk_f32 v18, v73, 0x3a800000, v228
	v_rsq_f32_e32 v20, v18
	s_waitcnt vmcnt(11)
	v_lshlrev_b32_e32 v24, 16, v58
	s_waitcnt lgkmcnt(1)
	v_mul_f32_e32 v10, 0xbfb8aa3b, v10
	v_mul_f32_e32 v11, 0xbfb8aa3b, v11
	v_exp_f32_e32 v10, v10
	v_exp_f32_e32 v11, v11
	v_mul_f32_e32 v12, 0xbfb8aa3b, v12
	v_mul_f32_e32 v13, 0xbfb8aa3b, v13
	v_exp_f32_e32 v12, v12
	v_exp_f32_e32 v13, v13
	v_add_f32_e32 v10, 1.0, v10
	v_add_f32_e32 v11, 1.0, v11
	v_rcp_f32_e32 v10, v10
	v_rcp_f32_e32 v11, v11
	v_and_b32_e32 v25, 0xffff0000, v58
	v_pk_mul_f32 v[24:25], v[20:21], v[24:25] op_sel_hi:[0,1]
	v_add_f32_e32 v12, 1.0, v12
	v_add_f32_e32 v13, 1.0, v13
	v_lshlrev_b32_e32 v22, 16, v60
	v_and_b32_e32 v23, 0xffff0000, v60
	v_pk_mul_f32 v[24:25], v[38:39], v[24:25]
	v_rcp_f32_e32 v12, v12
	v_rcp_f32_e32 v13, v13
	v_pk_fma_f32 v[10:11], v[24:25], v[10:11], v[22:23]
	v_lshlrev_b32_e32 v24, 16, v59
	v_and_b32_e32 v25, 0xffff0000, v59
	v_pk_mul_f32 v[24:25], v[20:21], v[24:25] op_sel_hi:[0,1]
	v_lshlrev_b32_e32 v22, 16, v61
	v_and_b32_e32 v23, 0xffff0000, v61
	v_pk_mul_f32 v[24:25], v[40:41], v[24:25]
	s_waitcnt vmcnt(8)
	v_fmamk_f32 v18, v90, 0x3a800000, v228
	v_pk_fma_f32 v[12:13], v[24:25], v[12:13], v[22:23]
	v_lshlrev_b64 v[22:23], 12, v[56:57]
	v_lshl_add_u64 v[22:23], s[54:55], 0, v[22:23]
	v_lshl_add_u64 v[22:23], v[22:23], 0, v[148:149]
	global_store_dwordx4 v[22:23], v[10:13], off nt
	v_rsq_f32_e32 v18, v18
	s_waitcnt lgkmcnt(0)
	v_mul_f32_e32 v10, 0xbfb8aa3b, v14
	v_mul_f32_e32 v11, 0xbfb8aa3b, v15
	v_exp_f32_e32 v10, v10
	v_exp_f32_e32 v11, v11
	s_waitcnt vmcnt(7)
	v_lshlrev_b32_e32 v14, 16, v54
	v_and_b32_e32 v15, 0xffff0000, v54
	v_add_f32_e32 v10, 1.0, v10
	v_add_f32_e32 v11, 1.0, v11
	v_rcp_f32_e32 v10, v10
	v_rcp_f32_e32 v11, v11
	v_pk_mul_f32 v[14:15], v[18:19], v[14:15] op_sel_hi:[0,1]
	v_lshlrev_b32_e32 v12, 16, v52
	v_and_b32_e32 v13, 0xffff0000, v52
	v_pk_mul_f32 v[14:15], v[38:39], v[14:15]
	s_nop 0
	v_pk_fma_f32 v[10:11], v[14:15], v[10:11], v[12:13]
	v_mul_f32_e32 v12, 0xbfb8aa3b, v16
	v_mul_f32_e32 v13, 0xbfb8aa3b, v17
	v_exp_f32_e32 v12, v12
	v_exp_f32_e32 v13, v13
	v_lshlrev_b32_e32 v16, 16, v55
	v_and_b32_e32 v17, 0xffff0000, v55
	v_add_f32_e32 v12, 1.0, v12
	v_add_f32_e32 v13, 1.0, v13
	v_rcp_f32_e32 v12, v12
	v_rcp_f32_e32 v13, v13
	v_pk_mul_f32 v[16:17], v[18:19], v[16:17] op_sel_hi:[0,1]
	v_lshlrev_b32_e32 v14, 16, v53
	v_and_b32_e32 v15, 0xffff0000, v53
	v_pk_mul_f32 v[16:17], v[40:41], v[16:17]
	s_nop 0
	v_pk_fma_f32 v[12:13], v[16:17], v[12:13], v[14:15]
	v_lshlrev_b64 v[14:15], 12, v[50:51]
	v_lshl_add_u64 v[14:15], s[54:55], 0, v[14:15]
	v_lshl_add_u64 v[14:15], v[14:15], 0, v[148:149]
	global_store_dwordx4 v[14:15], v[10:13], off nt
	ds_write_b128 v208, v[6:9]
	ds_write_b128 v208, v[2:5] offset:16
	ds_read_b128 v[2:5], v209
	ds_read_b128 v[6:9], v209 offset:1152
	v_lshlrev_b32_e32 v12, 16, v46
	v_and_b32_e32 v13, 0xffff0000, v46
	v_pk_mul_f32 v[12:13], v[20:21], v[12:13] op_sel_hi:[0,1]
	s_waitcnt lgkmcnt(1)
	v_mul_f32_e32 v2, 0xbfb8aa3b, v2
	v_mul_f32_e32 v3, 0xbfb8aa3b, v3
	v_exp_f32_e32 v2, v2
	v_exp_f32_e32 v3, v3
	v_mul_f32_e32 v4, 0xbfb8aa3b, v4
	v_mul_f32_e32 v5, 0xbfb8aa3b, v5
	v_exp_f32_e32 v4, v4
	v_exp_f32_e32 v5, v5
	v_add_f32_e32 v2, 1.0, v2
	v_add_f32_e32 v3, 1.0, v3
	v_rcp_f32_e32 v2, v2
	v_rcp_f32_e32 v3, v3
	v_add_f32_e32 v4, 1.0, v4
	v_add_f32_e32 v5, 1.0, v5
	v_lshlrev_b32_e32 v10, 16, v48
	v_and_b32_e32 v11, 0xffff0000, v48
	v_pk_mul_f32 v[12:13], v[26:27], v[12:13]
	v_rcp_f32_e32 v4, v4
	v_rcp_f32_e32 v5, v5
	v_pk_fma_f32 v[2:3], v[12:13], v[2:3], v[10:11]
	v_lshlrev_b32_e32 v12, 16, v47
	v_and_b32_e32 v13, 0xffff0000, v47
	v_pk_mul_f32 v[12:13], v[20:21], v[12:13] op_sel_hi:[0,1]
	v_lshlrev_b32_e32 v10, 16, v49
	v_and_b32_e32 v11, 0xffff0000, v49
	v_pk_mul_f32 v[12:13], v[28:29], v[12:13]
	s_nop 0
	v_pk_fma_f32 v[4:5], v[12:13], v[4:5], v[10:11]
	global_store_dwordx4 v[22:23], v[2:5], off offset:512 nt
	s_waitcnt lgkmcnt(0)
	s_nop 0
	v_mul_f32_e32 v2, 0xbfb8aa3b, v6
	v_mul_f32_e32 v3, 0xbfb8aa3b, v7
	v_exp_f32_e32 v2, v2
	v_exp_f32_e32 v3, v3
	s_waitcnt vmcnt(7)
	v_lshlrev_b32_e32 v4, 16, v44
	v_and_b32_e32 v5, 0xffff0000, v44
	v_add_f32_e32 v2, 1.0, v2
	v_add_f32_e32 v3, 1.0, v3
	v_rcp_f32_e32 v2, v2
	v_rcp_f32_e32 v3, v3
	v_pk_mul_f32 v[4:5], v[18:19], v[4:5] op_sel_hi:[0,1]
	v_pk_mul_f32 v[4:5], v[26:27], v[4:5]
	v_lshlrev_b32_e32 v6, 16, v42
	v_and_b32_e32 v7, 0xffff0000, v42
	v_pk_fma_f32 v[2:3], v[4:5], v[2:3], v[6:7]
	v_mul_f32_e32 v4, 0xbfb8aa3b, v8
	v_mul_f32_e32 v5, 0xbfb8aa3b, v9
	v_exp_f32_e32 v4, v4
	v_exp_f32_e32 v5, v5
	v_lshlrev_b32_e32 v6, 16, v45
	v_and_b32_e32 v7, 0xffff0000, v45
	v_add_f32_e32 v4, 1.0, v4
	v_add_f32_e32 v5, 1.0, v5
	v_rcp_f32_e32 v4, v4
	v_rcp_f32_e32 v5, v5
	v_pk_mul_f32 v[6:7], v[18:19], v[6:7] op_sel_hi:[0,1]
	v_lshlrev_b32_e32 v8, 16, v43
	v_and_b32_e32 v9, 0xffff0000, v43
	v_pk_mul_f32 v[6:7], v[28:29], v[6:7]
	s_nop 0
	v_pk_fma_f32 v[4:5], v[6:7], v[4:5], v[8:9]
	global_store_dwordx4 v[14:15], v[2:5], off offset:512 nt
	s_cbranch_scc1 .LBB0_898
	s_andn2_b64 vcc, exec, s[6:7]
	s_cbranch_vccnz .LBB0_897
	s_barrier
	s_branch .LBB0_897
